# no per-segment setprio in GEMM K-loops + merged vmcnt(8)/lgkmcnt(0) closing wait in each load segment
# speedup vs baseline: 1.0044x; 1.0044x over previous
; #define PG8_STAGE(bufoff, gbase, voff) do { _Pragma("unroll") for (int _i = 0; _i < 2; ++_i) \
;         __builtin_amdgcn_global_load_lds((const unsigned*)((const char*)(gbase) + (voff)[_i]), (PG8_LAS unsigned*)(lds + (bufoff) + ldsw + _i * 8192), 16, 0, 0); } while (0)
; #define PG8_LDA(dst, b, h) do { _Pragma("unroll") for (int m = 0; m < 4; ++m) _Pragma("unroll") for (int k = 0; k < 2; ++k) dst[m][k] = *(const PG8_LAS bf16x8*)(lds + PG8_SA(b, h) + aoff + m * 2048 + k * 1024); } while (0)
; #define PG8_LDB(dst, b, h) do { _Pragma("unroll") for (int n = 0; n < 2; ++n) _Pragma("unroll") for (int k = 0; k < 2; ++k) dst[n][k] = *(const PG8_LAS bf16x8*)(lds + PG8_SB(b, h) + boff + n * 2048 + k * 1024); } while (0)
; #define PG8_MMA(ai, bj, At, Bt) do { __builtin_amdgcn_s_setprio(1); _Pragma("unroll") for (int m = 0; m < 4; ++m) _Pragma("unroll") for (int n = 0; n < 2; ++n) _Pragma("unroll") for (int k = 0; k < 2; ++k) \
;         acc[ai][bj][m][n] = __builtin_amdgcn_mfma_f32_16x16x32_bf16(Bt[n][k], At[m][k], acc[ai][bj][m][n], 0, 0, 0); __builtin_amdgcn_s_setprio(0); } while (0)
; #define PG8_WAIT_V(n) asm volatile("s_waitcnt vmcnt(" #n ")" ::: "memory")
; #define PG8_WAIT_L(n) asm volatile("s_waitcnt lgkmcnt(" #n ")" ::: "memory")
; #define PG8_BAR __builtin_amdgcn_s_barrier()
; #define PG8_SCHED __builtin_amdgcn_sched_barrier(0)
; template <class Epi, class Sched, bool ALIGN_EPI = false, bool SP2 = false>
; __device__ __forceinline__ void gemm_phase(PG8_LAS unsigned char* lds, const Gemm g, const Sched& S, const Epi& E) {
;     ...
;             PG8_LDB(B0, 0, 0); PG8_LDB(B1, 0, 1); PG8_SCHED; PG8_LDA(At, 0, 0); PG8_STAGE(PG8_SA(1, 1), a1 + hstep, voffA);
;             PG8_WAIT_V(8); PG8_WAIT_L(0); PG8_BAR; PG8_MMA(0, 0, At, B0); PG8_MMA(0, 1, At, B1); PG8_BAR; PG8_SCHED;
;             PG8_LDA(At, 0, 1); PG8_STAGE(PG8_SB(0, 0), b2, voffB); PG8_STAGE(PG8_SB(0, 1), b2 + hstep, voffB); PG8_STAGE(PG8_SA(0, 0), a2, voffA);
;             PG8_WAIT_V(8); PG8_WAIT_L(0); PG8_BAR; PG8_MMA(1, 0, At, B0); PG8_MMA(1, 1, At, B1); PG8_BAR; PG8_SCHED;
.LBB0_265:
	s_add_u32 s10, s16, 0xfff80080
	s_addc_u32 s11, s17, -1
	s_add_i32 s27, 0, 0x10000
	s_cmp_eq_u32 s23, 28
	s_cselect_b32 s51, s5, s11
	s_cselect_b32 s50, s7, s10
	s_cselect_b32 s19, s8, s22
	s_cselect_b32 s18, s9, s15
	s_add_i32 s10, 0, 0x14000
	v_add_u32_e32 v168, s27, v157
	v_add_u32_e32 v184, s10, v157
	ds_read_b128 v[152:155], v168
	ds_read_b128 v[160:163], v168 offset:1024
	ds_read_b128 v[164:167], v168 offset:2048
	ds_read_b128 v[168:171], v168 offset:3072
	ds_read_b128 v[172:175], v184
	ds_read_b128 v[176:179], v184 offset:1024
	ds_read_b128 v[180:183], v184 offset:2048
	ds_read_b128 v[184:187], v184 offset:3072
	v_lshl_add_u64 v[200:201], s[16:17], 0, v[148:149]
	s_add_i32 m0, s57, 0xc000
	ds_read_b128 v[188:191], v159
	ds_read_b128 v[192:195], v159 offset:1024
	ds_read_b128 v[196:199], v159 offset:2048
	ds_read_b128 v[216:219], v159 offset:3072
	ds_read_b128 v[220:223], v159 offset:4096
	ds_read_b128 v[224:227], v159 offset:5120
	ds_read_b128 v[228:231], v159 offset:6144
	ds_read_b128 v[232:235], v159 offset:7168
	global_load_lds_dwordx4 v[200:201], off
	v_lshl_add_u64 v[200:201], s[16:17], 0, v[150:151]
	s_add_i32 m0, s57, 0xe000
	s_nop 0
	global_load_lds_dwordx4 v[200:201], off
	s_waitcnt vmcnt(8) lgkmcnt(0)
	s_barrier
	v_mfma_f32_16x16x32_bf16 v[126:129], v[152:155], v[188:191], v[126:129]
	v_mfma_f32_16x16x32_bf16 v[122:125], v[164:167], v[188:191], v[122:125]
	v_mfma_f32_16x16x32_bf16 v[110:113], v[152:155], v[196:199], v[110:113]
	v_mfma_f32_16x16x32_bf16 v[106:109], v[164:167], v[196:199], v[106:109]
	v_mfma_f32_16x16x32_bf16 v[94:97], v[152:155], v[220:223], v[94:97]
	v_mfma_f32_16x16x32_bf16 v[90:93], v[164:167], v[220:223], v[90:93]
	v_mfma_f32_16x16x32_bf16 v[78:81], v[152:155], v[228:231], v[78:81]
	v_mfma_f32_16x16x32_bf16 v[74:77], v[164:167], v[228:231], v[74:77]
	v_mfma_f32_16x16x32_bf16 v[126:129], v[160:163], v[192:195], v[126:129]
	v_mfma_f32_16x16x32_bf16 v[122:125], v[168:171], v[192:195], v[122:125]
	v_mfma_f32_16x16x32_bf16 v[110:113], v[160:163], v[216:219], v[110:113]
	v_mfma_f32_16x16x32_bf16 v[106:109], v[168:171], v[216:219], v[106:109]
	v_mfma_f32_16x16x32_bf16 v[94:97], v[160:163], v[224:227], v[94:97]
	v_mfma_f32_16x16x32_bf16 v[90:93], v[168:171], v[224:227], v[90:93]
	v_mfma_f32_16x16x32_bf16 v[78:81], v[160:163], v[232:235], v[78:81]
	v_mfma_f32_16x16x32_bf16 v[74:77], v[168:171], v[232:235], v[74:77]
	v_mfma_f32_16x16x32_bf16 v[118:121], v[172:175], v[188:191], v[118:121]
	v_mfma_f32_16x16x32_bf16 v[114:117], v[180:183], v[188:191], v[114:117]
	v_mfma_f32_16x16x32_bf16 v[102:105], v[172:175], v[196:199], v[102:105]
	v_mfma_f32_16x16x32_bf16 v[98:101], v[180:183], v[196:199], v[98:101]
	v_mfma_f32_16x16x32_bf16 v[86:89], v[172:175], v[220:223], v[86:89]
	v_mfma_f32_16x16x32_bf16 v[82:85], v[180:183], v[220:223], v[82:85]
	v_mfma_f32_16x16x32_bf16 v[70:73], v[172:175], v[228:231], v[70:73]
	v_mfma_f32_16x16x32_bf16 v[66:69], v[180:183], v[228:231], v[66:69]
	v_mfma_f32_16x16x32_bf16 v[118:121], v[176:179], v[192:195], v[118:121]
	v_mfma_f32_16x16x32_bf16 v[114:117], v[184:187], v[192:195], v[114:117]
	v_mfma_f32_16x16x32_bf16 v[102:105], v[176:179], v[216:219], v[102:105]
	v_mfma_f32_16x16x32_bf16 v[98:101], v[184:187], v[216:219], v[98:101]
	v_mfma_f32_16x16x32_bf16 v[86:89], v[176:179], v[224:227], v[86:89]
	v_mfma_f32_16x16x32_bf16 v[82:85], v[184:187], v[224:227], v[82:85]
	v_mfma_f32_16x16x32_bf16 v[70:73], v[176:179], v[232:235], v[70:73]
	v_mfma_f32_16x16x32_bf16 v[66:69], v[184:187], v[232:235], v[66:69]
	s_barrier
	s_add_i32 s11, s27, s56
	v_lshl_add_u64 v[200:201], s[18:19], 0, v[0:1]
	s_mov_b32 m0, s11
	ds_read_b128 v[188:191], v159 offset:16384
	ds_read_b128 v[192:195], v159 offset:17408
	ds_read_b128 v[196:199], v159 offset:18432
	ds_read_b128 v[216:219], v159 offset:19456
	ds_read_b128 v[220:223], v159 offset:20480
	ds_read_b128 v[224:227], v159 offset:21504
	ds_read_b128 v[228:231], v159 offset:22528
	ds_read_b128 v[232:235], v159 offset:23552
	global_load_lds_dwordx4 v[200:201], off
	s_add_i32 m0, s11, 0x2000
	s_add_u32 s38, s18, 0x80000
	v_lshl_add_u64 v[236:237], s[18:19], 0, v[142:143]
	s_addc_u32 s39, s19, 0
	s_add_i32 s10, s10, s56
	global_load_lds_dwordx4 v[236:237], off
	v_lshl_add_u64 v[238:239], s[38:39], 0, v[0:1]
	s_mov_b32 m0, s10
	v_lshl_add_u64 v[240:241], s[50:51], 0, v[144:145]
	global_load_lds_dwordx4 v[238:239], off
	v_lshl_add_u64 v[238:239], s[38:39], 0, v[142:143]
	s_add_i32 m0, s10, 0x2000
	s_nop 0
	global_load_lds_dwordx4 v[238:239], off
	v_lshl_add_u64 v[238:239], s[50:51], 0, v[146:147]
	s_mov_b32 m0, s57
	s_nop 0
	global_load_lds_dwordx4 v[238:239], off
	s_mov_b32 m0, s58
	s_nop 0
	global_load_lds_dwordx4 v[240:241], off
	s_waitcnt vmcnt(8) lgkmcnt(0)
	s_barrier
; #define PG8_STAGE(bufoff, gbase, voff) do { _Pragma("unroll") for (int _i = 0; _i < 2; ++_i) \
;         __builtin_amdgcn_global_load_lds((const unsigned*)((const char*)(gbase) + (voff)[_i]), (PG8_LAS unsigned*)(lds + (bufoff) + ldsw + _i * 8192), 16, 0, 0); } while (0)
; #define PG8_LDA(dst, b, h) do { _Pragma("unroll") for (int m = 0; m < 4; ++m) _Pragma("unroll") for (int k = 0; k < 2; ++k) dst[m][k] = *(const PG8_LAS bf16x8*)(lds + PG8_SA(b, h) + aoff + m * 2048 + k * 1024); } while (0)
; #define PG8_LDB(dst, b, h) do { _Pragma("unroll") for (int n = 0; n < 2; ++n) _Pragma("unroll") for (int k = 0; k < 2; ++k) dst[n][k] = *(const PG8_LAS bf16x8*)(lds + PG8_SB(b, h) + boff + n * 2048 + k * 1024); } while (0)
; #define PG8_MMA(ai, bj, At, Bt) do { __builtin_amdgcn_s_setprio(1); _Pragma("unroll") for (int m = 0; m < 4; ++m) _Pragma("unroll") for (int n = 0; n < 2; ++n) _Pragma("unroll") for (int k = 0; k < 2; ++k) \
;         acc[ai][bj][m][n] = __builtin_amdgcn_mfma_f32_16x16x32_bf16(Bt[n][k], At[m][k], acc[ai][bj][m][n], 0, 0, 0); __builtin_amdgcn_s_setprio(0); } while (0)
; #define PG8_WAIT_V(n) asm volatile("s_waitcnt vmcnt(" #n ")" ::: "memory")
; #define PG8_WAIT_L(n) asm volatile("s_waitcnt lgkmcnt(" #n ")" ::: "memory")
; #define PG8_BAR __builtin_amdgcn_s_barrier()
; #define PG8_SCHED __builtin_amdgcn_sched_barrier(0)
; template <class Epi, class Sched, bool ALIGN_EPI = false, bool SP2 = false>
; __device__ __forceinline__ void gemm_phase(PG8_LAS unsigned char* lds, const Gemm g, const Sched& S, const Epi& E) {
;     ...
;             PG8_WAIT_V(8); PG8_WAIT_L(0); PG8_BAR; PG8_MMA(1, 0, At, B0); PG8_MMA(1, 1, At, B1); PG8_BAR; PG8_SCHED;
;             PG8_LDB(B0, 1, 0); PG8_LDB(B1, 1, 1); PG8_SCHED; PG8_LDA(At, 1, 0); PG8_STAGE(PG8_SA(0, 1), a2 + hstep, voffA);
;             PG8_WAIT_V(8); PG8_WAIT_L(0); PG8_BAR; PG8_MMA(0, 0, At, B0); PG8_MMA(0, 1, At, B1); PG8_BAR; PG8_SCHED;
;             PG8_LDA(At, 1, 1); PG8_STAGE(PG8_SB(1, 0), b3, voffB); PG8_STAGE(PG8_SB(1, 1), b3 + hstep, voffB); PG8_STAGE(PG8_SA(1, 0), a3, voffA);
;             PG8_WAIT_V(8); PG8_WAIT_L(0); PG8_BAR; PG8_MMA(1, 0, At, B0); PG8_MMA(1, 1, At, B1); PG8_BAR; PG8_SCHED;
	v_mfma_f32_16x16x32_bf16 v[62:65], v[152:155], v[188:191], v[62:65]
	v_mfma_f32_16x16x32_bf16 v[58:61], v[164:167], v[188:191], v[58:61]
	v_mfma_f32_16x16x32_bf16 v[50:53], v[152:155], v[196:199], v[50:53]
	v_mfma_f32_16x16x32_bf16 v[42:45], v[164:167], v[196:199], v[42:45]
	v_mfma_f32_16x16x32_bf16 v[34:37], v[152:155], v[220:223], v[34:37]
	v_mfma_f32_16x16x32_bf16 v[26:29], v[164:167], v[220:223], v[26:29]
	v_mfma_f32_16x16x32_bf16 v[18:21], v[152:155], v[228:231], v[18:21]
	v_mfma_f32_16x16x32_bf16 v[10:13], v[164:167], v[228:231], v[10:13]
	v_mfma_f32_16x16x32_bf16 v[62:65], v[160:163], v[192:195], v[62:65]
	v_mfma_f32_16x16x32_bf16 v[58:61], v[168:171], v[192:195], v[58:61]
	v_mfma_f32_16x16x32_bf16 v[50:53], v[160:163], v[216:219], v[50:53]
	v_mfma_f32_16x16x32_bf16 v[42:45], v[168:171], v[216:219], v[42:45]
	v_mfma_f32_16x16x32_bf16 v[34:37], v[160:163], v[224:227], v[34:37]
	v_mfma_f32_16x16x32_bf16 v[26:29], v[168:171], v[224:227], v[26:29]
	v_mfma_f32_16x16x32_bf16 v[18:21], v[160:163], v[232:235], v[18:21]
	v_mfma_f32_16x16x32_bf16 v[10:13], v[168:171], v[232:235], v[10:13]
	v_mfma_f32_16x16x32_bf16 v[54:57], v[172:175], v[188:191], v[54:57]
	v_mfma_f32_16x16x32_bf16 v[46:49], v[180:183], v[188:191], v[46:49]
	v_mfma_f32_16x16x32_bf16 v[38:41], v[172:175], v[196:199], v[38:41]
	v_mfma_f32_16x16x32_bf16 v[30:33], v[180:183], v[196:199], v[30:33]
	v_mfma_f32_16x16x32_bf16 v[22:25], v[172:175], v[220:223], v[22:25]
	v_mfma_f32_16x16x32_bf16 v[14:17], v[180:183], v[220:223], v[14:17]
	v_mfma_f32_16x16x32_bf16 v[6:9], v[172:175], v[228:231], v[6:9]
	v_mfma_f32_16x16x32_bf16 v[2:5], v[180:183], v[228:231], v[2:5]
	v_mfma_f32_16x16x32_bf16 v[54:57], v[176:179], v[192:195], v[54:57]
	v_mfma_f32_16x16x32_bf16 v[46:49], v[184:187], v[192:195], v[46:49]
	v_mfma_f32_16x16x32_bf16 v[38:41], v[176:179], v[216:219], v[38:41]
	v_mfma_f32_16x16x32_bf16 v[30:33], v[184:187], v[216:219], v[30:33]
	v_mfma_f32_16x16x32_bf16 v[22:25], v[176:179], v[224:227], v[22:25]
	v_mfma_f32_16x16x32_bf16 v[14:17], v[184:187], v[224:227], v[14:17]
	v_mfma_f32_16x16x32_bf16 v[6:9], v[176:179], v[232:235], v[6:9]
	v_mfma_f32_16x16x32_bf16 v[2:5], v[184:187], v[232:235], v[2:5]
	s_barrier
	s_add_i32 s10, 0, 0x18000
	s_add_i32 s11, 0, 0x1c000
	v_add_u32_e32 v168, s10, v157
	v_add_u32_e32 v184, s11, v157
	ds_read_b128 v[152:155], v168
	ds_read_b128 v[160:163], v168 offset:1024
	ds_read_b128 v[164:167], v168 offset:2048
	ds_read_b128 v[168:171], v168 offset:3072
	ds_read_b128 v[172:175], v184
	ds_read_b128 v[176:179], v184 offset:1024
	ds_read_b128 v[180:183], v184 offset:2048
	ds_read_b128 v[184:187], v184 offset:3072
	s_add_u32 s38, s50, 0x80000
	s_addc_u32 s39, s51, 0
	s_mov_b32 m0, s59
	v_lshl_add_u64 v[242:243], s[38:39], 0, v[146:147]
	ds_read_b128 v[188:191], v159 offset:32768
	ds_read_b128 v[192:195], v159 offset:33792
	ds_read_b128 v[196:199], v159 offset:34816
	ds_read_b128 v[216:219], v159 offset:35840
	ds_read_b128 v[220:223], v159 offset:36864
	ds_read_b128 v[224:227], v159 offset:37888
	ds_read_b128 v[228:231], v159 offset:38912
	ds_read_b128 v[232:235], v159 offset:39936
	global_load_lds_dwordx4 v[242:243], off
	v_lshl_add_u64 v[242:243], s[38:39], 0, v[144:145]
	s_mov_b32 m0, s60
	s_nop 0
	global_load_lds_dwordx4 v[242:243], off
	s_waitcnt vmcnt(8) lgkmcnt(0)
	s_barrier
	v_mfma_f32_16x16x32_bf16 v[126:129], v[152:155], v[188:191], v[126:129]
	v_mfma_f32_16x16x32_bf16 v[122:125], v[164:167], v[188:191], v[122:125]
	v_mfma_f32_16x16x32_bf16 v[110:113], v[152:155], v[196:199], v[110:113]
	v_mfma_f32_16x16x32_bf16 v[106:109], v[164:167], v[196:199], v[106:109]
	v_mfma_f32_16x16x32_bf16 v[94:97], v[152:155], v[220:223], v[94:97]
	v_mfma_f32_16x16x32_bf16 v[90:93], v[164:167], v[220:223], v[90:93]
	v_mfma_f32_16x16x32_bf16 v[78:81], v[152:155], v[228:231], v[78:81]
	v_mfma_f32_16x16x32_bf16 v[74:77], v[164:167], v[228:231], v[74:77]
	v_mfma_f32_16x16x32_bf16 v[126:129], v[160:163], v[192:195], v[126:129]
	v_mfma_f32_16x16x32_bf16 v[122:125], v[168:171], v[192:195], v[122:125]
	v_mfma_f32_16x16x32_bf16 v[110:113], v[160:163], v[216:219], v[110:113]
	v_mfma_f32_16x16x32_bf16 v[106:109], v[168:171], v[216:219], v[106:109]
	v_mfma_f32_16x16x32_bf16 v[94:97], v[160:163], v[224:227], v[94:97]
	v_mfma_f32_16x16x32_bf16 v[90:93], v[168:171], v[224:227], v[90:93]
	v_mfma_f32_16x16x32_bf16 v[78:81], v[160:163], v[232:235], v[78:81]
	v_mfma_f32_16x16x32_bf16 v[74:77], v[168:171], v[232:235], v[74:77]
	v_mfma_f32_16x16x32_bf16 v[118:121], v[172:175], v[188:191], v[118:121]
	v_mfma_f32_16x16x32_bf16 v[114:117], v[180:183], v[188:191], v[114:117]
	v_mfma_f32_16x16x32_bf16 v[102:105], v[172:175], v[196:199], v[102:105]
	v_mfma_f32_16x16x32_bf16 v[98:101], v[180:183], v[196:199], v[98:101]
	v_mfma_f32_16x16x32_bf16 v[86:89], v[172:175], v[220:223], v[86:89]
	v_mfma_f32_16x16x32_bf16 v[82:85], v[180:183], v[220:223], v[82:85]
	v_mfma_f32_16x16x32_bf16 v[70:73], v[172:175], v[228:231], v[70:73]
	v_mfma_f32_16x16x32_bf16 v[66:69], v[180:183], v[228:231], v[66:69]
	v_mfma_f32_16x16x32_bf16 v[118:121], v[176:179], v[192:195], v[118:121]
	v_mfma_f32_16x16x32_bf16 v[114:117], v[184:187], v[192:195], v[114:117]
	v_mfma_f32_16x16x32_bf16 v[102:105], v[176:179], v[216:219], v[102:105]
	v_mfma_f32_16x16x32_bf16 v[98:101], v[184:187], v[216:219], v[98:101]
	v_mfma_f32_16x16x32_bf16 v[86:89], v[176:179], v[224:227], v[86:89]
	v_mfma_f32_16x16x32_bf16 v[82:85], v[184:187], v[224:227], v[82:85]
	v_mfma_f32_16x16x32_bf16 v[70:73], v[176:179], v[232:235], v[70:73]
	v_mfma_f32_16x16x32_bf16 v[66:69], v[184:187], v[232:235], v[66:69]
	s_barrier
; #define PG8_STAGE(bufoff, gbase, voff) do { _Pragma("unroll") for (int _i = 0; _i < 2; ++_i) \
;         __builtin_amdgcn_global_load_lds((const unsigned*)((const char*)(gbase) + (voff)[_i]), (PG8_LAS unsigned*)(lds + (bufoff) + ldsw + _i * 8192), 16, 0, 0); } while (0)
; #define PG8_LDA(dst, b, h) do { _Pragma("unroll") for (int m = 0; m < 4; ++m) _Pragma("unroll") for (int k = 0; k < 2; ++k) dst[m][k] = *(const PG8_LAS bf16x8*)(lds + PG8_SA(b, h) + aoff + m * 2048 + k * 1024); } while (0)
; #define PG8_WAIT_V(n) asm volatile("s_waitcnt vmcnt(" #n ")" ::: "memory")
; template <class Epi, class Sched, bool ALIGN_EPI = false, bool SP2 = false>
; __device__ __forceinline__ void gemm_phase(PG8_LAS unsigned char* lds, const Gemm g, const Sched& S, const Epi& E) {
;     ...
;             PG8_LDA(At, 1, 1); PG8_STAGE(PG8_SB(1, 0), b3, voffB); PG8_STAGE(PG8_SB(1, 1), b3 + hstep, voffB); PG8_STAGE(PG8_SA(1, 0), a3, voffA);
;             PG8_WAIT_V(8); PG8_WAIT_L(0); PG8_BAR; PG8_MMA(1, 0, At, B0); PG8_MMA(1, 1, At, B1); PG8_BAR; PG8_SCHED;
;             } else {
;             PG8_LDB(B0, 0, 0); PG8_SCHED; PG8_LDA(At, 0, 0); PG8_STAGE(PG8_SA(1, 1), a1 + hstep, voffA);
;             PG8_WAIT_L(8); PG8_BAR; PG8_WAIT_L(0); PG8_MMA(0, 0, At, B0); PG8_BAR; PG8_SCHED;
;             PG8_LDB(B1, 0, 1); PG8_STAGE(PG8_SB(0, 0), b2, voffB);
;             PG8_BAR; PG8_WAIT_L(0); PG8_MMA(0, 1, At, B1); PG8_BAR;
;             PG8_LDA(At, 0, 1); PG8_STAGE(PG8_SA(0, 0), a2, voffA);
;             PG8_BAR; PG8_WAIT_L(0); PG8_MMA(1, 0, At, B0); PG8_BAR; PG8_SCHED;
;             PG8_STAGE(PG8_SB(0, 1), b2 + hstep, voffB);
;             PG8_WAIT_V(6); PG8_BAR; PG8_MMA(1, 1, At, B1); PG8_BAR;
;             PG8_LDB(B0, 1, 0); PG8_SCHED; PG8_LDA(At, 1, 0); PG8_STAGE(PG8_SA(0, 1), a2 + hstep, voffA);
;             PG8_WAIT_L(8); PG8_BAR; PG8_WAIT_L(0); PG8_MMA(0, 0, At, B0); PG8_BAR; PG8_SCHED;
;             PG8_LDB(B1, 1, 1); PG8_STAGE(PG8_SB(1, 0), b3, voffB);
;             PG8_BAR; PG8_WAIT_L(0); PG8_MMA(0, 1, At, B1); PG8_BAR;
;             PG8_LDA(At, 1, 1); PG8_STAGE(PG8_SA(1, 0), a3, voffA);
;             PG8_BAR; PG8_WAIT_L(0); PG8_MMA(1, 0, At, B0); PG8_BAR; PG8_SCHED;
;             PG8_STAGE(PG8_SB(1, 1), b3 + hstep, voffB);
;             PG8_WAIT_V(6); PG8_BAR; PG8_MMA(1, 1, At, B1); PG8_BAR;
;             }
;         }
;         if constexpr (ALIGN_EPI) { if (wr == 0) PG8_BAR; }
	s_add_i32 s10, s10, s56
	v_lshl_add_u64 v[200:201], v[200:201], 0, s[30:31]
	s_mov_b32 m0, s10
	ds_read_b128 v[188:191], v159 offset:49152
	ds_read_b128 v[192:195], v159 offset:50176
	ds_read_b128 v[196:199], v159 offset:51200
	ds_read_b128 v[216:219], v159 offset:52224
	ds_read_b128 v[220:223], v159 offset:53248
	ds_read_b128 v[224:227], v159 offset:54272
	ds_read_b128 v[228:231], v159 offset:55296
	ds_read_b128 v[232:235], v159 offset:56320
	global_load_lds_dwordx4 v[200:201], off
	s_add_i32 m0, s10, 0x2000
	s_add_u32 s18, s18, 0x80080
	v_lshl_add_u64 v[200:201], v[236:237], 0, s[30:31]
	s_addc_u32 s19, s19, 0
	s_add_i32 s10, s11, s56
	global_load_lds_dwordx4 v[200:201], off
	v_lshl_add_u64 v[200:201], s[18:19], 0, v[0:1]
	s_mov_b32 m0, s10
	s_nop 0
	global_load_lds_dwordx4 v[200:201], off
	v_lshl_add_u64 v[200:201], s[18:19], 0, v[142:143]
	s_add_i32 m0, s10, 0x2000
	s_nop 0
	global_load_lds_dwordx4 v[200:201], off
	v_lshl_add_u64 v[200:201], v[238:239], 0, s[30:31]
	s_mov_b32 m0, s61
	s_nop 0
	global_load_lds_dwordx4 v[200:201], off
	v_lshl_add_u64 v[200:201], v[240:241], 0, s[30:31]
	s_mov_b32 m0, s62
	s_nop 0
	global_load_lds_dwordx4 v[200:201], off
	s_waitcnt vmcnt(8) lgkmcnt(0)
	s_barrier
	v_mfma_f32_16x16x32_bf16 v[62:65], v[152:155], v[188:191], v[62:65]
	v_mfma_f32_16x16x32_bf16 v[58:61], v[164:167], v[188:191], v[58:61]
	v_mfma_f32_16x16x32_bf16 v[50:53], v[152:155], v[196:199], v[50:53]
	v_mfma_f32_16x16x32_bf16 v[42:45], v[164:167], v[196:199], v[42:45]
	v_mfma_f32_16x16x32_bf16 v[34:37], v[152:155], v[220:223], v[34:37]
	v_mfma_f32_16x16x32_bf16 v[26:29], v[164:167], v[220:223], v[26:29]
	v_mfma_f32_16x16x32_bf16 v[18:21], v[152:155], v[228:231], v[18:21]
	v_mfma_f32_16x16x32_bf16 v[10:13], v[164:167], v[228:231], v[10:13]
	v_mfma_f32_16x16x32_bf16 v[62:65], v[160:163], v[192:195], v[62:65]
	v_mfma_f32_16x16x32_bf16 v[58:61], v[168:171], v[192:195], v[58:61]
	v_mfma_f32_16x16x32_bf16 v[50:53], v[160:163], v[216:219], v[50:53]
	v_mfma_f32_16x16x32_bf16 v[42:45], v[168:171], v[216:219], v[42:45]
	v_mfma_f32_16x16x32_bf16 v[34:37], v[160:163], v[224:227], v[34:37]
	v_mfma_f32_16x16x32_bf16 v[26:29], v[168:171], v[224:227], v[26:29]
	v_mfma_f32_16x16x32_bf16 v[18:21], v[160:163], v[232:235], v[18:21]
	v_mfma_f32_16x16x32_bf16 v[10:13], v[168:171], v[232:235], v[10:13]
	v_mfma_f32_16x16x32_bf16 v[54:57], v[172:175], v[188:191], v[54:57]
	v_mfma_f32_16x16x32_bf16 v[46:49], v[180:183], v[188:191], v[46:49]
	v_mfma_f32_16x16x32_bf16 v[38:41], v[172:175], v[196:199], v[38:41]
	v_mfma_f32_16x16x32_bf16 v[30:33], v[180:183], v[196:199], v[30:33]
	v_mfma_f32_16x16x32_bf16 v[22:25], v[172:175], v[220:223], v[22:25]
	v_mfma_f32_16x16x32_bf16 v[14:17], v[180:183], v[220:223], v[14:17]
	v_mfma_f32_16x16x32_bf16 v[6:9], v[172:175], v[228:231], v[6:9]
	v_mfma_f32_16x16x32_bf16 v[2:5], v[180:183], v[228:231], v[2:5]
	v_mfma_f32_16x16x32_bf16 v[54:57], v[176:179], v[192:195], v[54:57]
	v_mfma_f32_16x16x32_bf16 v[46:49], v[184:187], v[192:195], v[46:49]
	v_mfma_f32_16x16x32_bf16 v[38:41], v[176:179], v[216:219], v[38:41]
	v_mfma_f32_16x16x32_bf16 v[30:33], v[184:187], v[216:219], v[30:33]
	v_mfma_f32_16x16x32_bf16 v[22:25], v[176:179], v[224:227], v[22:25]
	v_mfma_f32_16x16x32_bf16 v[14:17], v[184:187], v[224:227], v[14:17]
	v_mfma_f32_16x16x32_bf16 v[6:9], v[176:179], v[232:235], v[6:9]
	v_mfma_f32_16x16x32_bf16 v[2:5], v[184:187], v[232:235], v[2:5]
	s_barrier
	s_add_i32 s23, s23, 2
	s_add_u32 s16, s16, 0x100
	s_addc_u32 s17, s17, 0
	s_add_u32 s15, s15, 0x100
	s_addc_u32 s22, s22, 0
	s_cmp_gt_u32 s23, 29
	s_cbranch_scc0 .LBB0_265
	s_and_b64 vcc, exec, s[24:25]
	s_cbranch_vccz .LBB0_268
	s_barrier

; #define PG8_STAGE(bufoff, gbase, voff) do { _Pragma("unroll") for (int _i = 0; _i < 2; ++_i) \
;         __builtin_amdgcn_global_load_lds((const unsigned*)((const char*)(gbase) + (voff)[_i]), (PG8_LAS unsigned*)(lds + (bufoff) + ldsw + _i * 8192), 16, 0, 0); } while (0)
; #define PG8_LDA(dst, b, h) do { _Pragma("unroll") for (int m = 0; m < 4; ++m) _Pragma("unroll") for (int k = 0; k < 2; ++k) dst[m][k] = *(const PG8_LAS bf16x8*)(lds + PG8_SA(b, h) + aoff + m * 2048 + k * 1024); } while (0)
; #define PG8_LDB(dst, b, h) do { _Pragma("unroll") for (int n = 0; n < 2; ++n) _Pragma("unroll") for (int k = 0; k < 2; ++k) dst[n][k] = *(const PG8_LAS bf16x8*)(lds + PG8_SB(b, h) + boff + n * 2048 + k * 1024); } while (0)
; #define PG8_MMA(ai, bj, At, Bt) do { __builtin_amdgcn_s_setprio(1); _Pragma("unroll") for (int m = 0; m < 4; ++m) _Pragma("unroll") for (int n = 0; n < 2; ++n) _Pragma("unroll") for (int k = 0; k < 2; ++k) \
;         acc[ai][bj][m][n] = __builtin_amdgcn_mfma_f32_16x16x32_bf16(Bt[n][k], At[m][k], acc[ai][bj][m][n], 0, 0, 0); __builtin_amdgcn_s_setprio(0); } while (0)
; #define PG8_WAIT_V(n) asm volatile("s_waitcnt vmcnt(" #n ")" ::: "memory")
; #define PG8_WAIT_L(n) asm volatile("s_waitcnt lgkmcnt(" #n ")" ::: "memory")
; #define PG8_BAR __builtin_amdgcn_s_barrier()
; #define PG8_SCHED __builtin_amdgcn_sched_barrier(0)
; template <class Epi, class Sched, bool ALIGN_EPI = false, bool SP2 = false>
; __device__ __forceinline__ void gemm_phase(PG8_LAS unsigned char* lds, const Gemm g, const Sched& S, const Epi& E) {
;     ...
;             PG8_LDB(B0, 0, 0); PG8_LDB(B1, 0, 1); PG8_SCHED; PG8_LDA(At, 0, 0); PG8_STAGE(PG8_SA(1, 1), a1 + hstep, voffA);
;             PG8_WAIT_V(8); PG8_WAIT_L(0); PG8_BAR; PG8_MMA(0, 0, At, B0); PG8_MMA(0, 1, At, B1); PG8_BAR; PG8_SCHED;
;             PG8_LDA(At, 0, 1); PG8_STAGE(PG8_SB(0, 0), b2, voffB); PG8_STAGE(PG8_SB(0, 1), b2 + hstep, voffB); PG8_STAGE(PG8_SA(0, 0), a2, voffA);
;             PG8_WAIT_V(8); PG8_WAIT_L(0); PG8_BAR; PG8_MMA(1, 0, At, B0); PG8_MMA(1, 1, At, B1); PG8_BAR; PG8_SCHED;
.LBB0_601:
	s_add_u32 s18, s16, 0x100
	s_addc_u32 s19, s17, 0
	s_add_i32 s10, 0, 0x10000
	s_cmp_eq_u32 s22, 28
	s_cselect_b32 s27, s5, s19
	s_cselect_b32 s26, s7, s18
	s_cselect_b32 s25, s8, s15
	s_cselect_b32 s24, s9, s14
	s_add_i32 s12, 0, 0x14000
	v_add_u32_e32 v160, s10, v187
	v_add_u32_e32 v176, s12, v187
	ds_read_b128 v[148:151], v160
	ds_read_b128 v[152:155], v160 offset:1024
	ds_read_b128 v[156:159], v160 offset:2048
	ds_read_b128 v[160:163], v160 offset:3072
	ds_read_b128 v[164:167], v176
	ds_read_b128 v[168:171], v176 offset:1024
	ds_read_b128 v[172:175], v176 offset:2048
	ds_read_b128 v[176:179], v176 offset:3072
	v_lshl_add_u64 v[184:185], s[16:17], 0, v[144:145]
	s_add_i32 m0, s61, 0xc000
	ds_read_b128 v[180:183], v189
	ds_read_b128 v[190:193], v189 offset:1024
	ds_read_b128 v[194:197], v189 offset:2048
	ds_read_b128 v[198:201], v189 offset:3072
	ds_read_b128 v[216:219], v189 offset:4096
	ds_read_b128 v[220:223], v189 offset:5120
	ds_read_b128 v[224:227], v189 offset:6144
	ds_read_b128 v[228:231], v189 offset:7168
	global_load_lds_dwordx4 v[184:185], off
	v_lshl_add_u64 v[184:185], s[16:17], 0, v[146:147]
	s_add_i32 m0, s61, 0xe000
	s_nop 0
	global_load_lds_dwordx4 v[184:185], off
	s_waitcnt vmcnt(8) lgkmcnt(0)
	s_barrier
	v_mfma_f32_16x16x32_bf16 v[126:129], v[148:151], v[180:183], v[126:129]
	v_mfma_f32_16x16x32_bf16 v[122:125], v[156:159], v[180:183], v[122:125]
	v_mfma_f32_16x16x32_bf16 v[110:113], v[148:151], v[194:197], v[110:113]
	v_mfma_f32_16x16x32_bf16 v[106:109], v[156:159], v[194:197], v[106:109]
	v_mfma_f32_16x16x32_bf16 v[94:97], v[148:151], v[216:219], v[94:97]
	v_mfma_f32_16x16x32_bf16 v[90:93], v[156:159], v[216:219], v[90:93]
	v_mfma_f32_16x16x32_bf16 v[78:81], v[148:151], v[224:227], v[78:81]
	v_mfma_f32_16x16x32_bf16 v[74:77], v[156:159], v[224:227], v[74:77]
	v_mfma_f32_16x16x32_bf16 v[126:129], v[152:155], v[190:193], v[126:129]
	v_mfma_f32_16x16x32_bf16 v[122:125], v[160:163], v[190:193], v[122:125]
	v_mfma_f32_16x16x32_bf16 v[110:113], v[152:155], v[198:201], v[110:113]
	v_mfma_f32_16x16x32_bf16 v[106:109], v[160:163], v[198:201], v[106:109]
	v_mfma_f32_16x16x32_bf16 v[94:97], v[152:155], v[220:223], v[94:97]
	v_mfma_f32_16x16x32_bf16 v[90:93], v[160:163], v[220:223], v[90:93]
	v_mfma_f32_16x16x32_bf16 v[78:81], v[152:155], v[228:231], v[78:81]
	v_mfma_f32_16x16x32_bf16 v[74:77], v[160:163], v[228:231], v[74:77]
	v_mfma_f32_16x16x32_bf16 v[118:121], v[164:167], v[180:183], v[118:121]
	v_mfma_f32_16x16x32_bf16 v[114:117], v[172:175], v[180:183], v[114:117]
	v_mfma_f32_16x16x32_bf16 v[102:105], v[164:167], v[194:197], v[102:105]
	v_mfma_f32_16x16x32_bf16 v[98:101], v[172:175], v[194:197], v[98:101]
	v_mfma_f32_16x16x32_bf16 v[86:89], v[164:167], v[216:219], v[86:89]
	v_mfma_f32_16x16x32_bf16 v[82:85], v[172:175], v[216:219], v[82:85]
	v_mfma_f32_16x16x32_bf16 v[70:73], v[164:167], v[224:227], v[70:73]
	v_mfma_f32_16x16x32_bf16 v[66:69], v[172:175], v[224:227], v[66:69]
	v_mfma_f32_16x16x32_bf16 v[118:121], v[168:171], v[190:193], v[118:121]
	v_mfma_f32_16x16x32_bf16 v[114:117], v[176:179], v[190:193], v[114:117]
	v_mfma_f32_16x16x32_bf16 v[102:105], v[168:171], v[198:201], v[102:105]
	v_mfma_f32_16x16x32_bf16 v[98:101], v[176:179], v[198:201], v[98:101]
	v_mfma_f32_16x16x32_bf16 v[86:89], v[168:171], v[220:223], v[86:89]
	v_mfma_f32_16x16x32_bf16 v[82:85], v[176:179], v[220:223], v[82:85]
	v_mfma_f32_16x16x32_bf16 v[70:73], v[168:171], v[228:231], v[70:73]
	v_mfma_f32_16x16x32_bf16 v[66:69], v[176:179], v[228:231], v[66:69]
	s_barrier
	s_add_i32 s10, s10, s60
	v_lshl_add_u64 v[184:185], s[24:25], 0, v[0:1]
	s_mov_b32 m0, s10
	ds_read_b128 v[180:183], v189 offset:16384
	ds_read_b128 v[190:193], v189 offset:17408
	ds_read_b128 v[194:197], v189 offset:18432
	ds_read_b128 v[198:201], v189 offset:19456
	ds_read_b128 v[216:219], v189 offset:20480
	ds_read_b128 v[220:223], v189 offset:21504
	ds_read_b128 v[224:227], v189 offset:22528
	ds_read_b128 v[228:231], v189 offset:23552
	global_load_lds_dwordx4 v[184:185], off
	s_add_i32 m0, s10, 0x2000
	s_add_u32 s10, s24, 0x80000
	v_lshl_add_u64 v[232:233], s[24:25], 0, v[142:143]
	s_addc_u32 s11, s25, 0
	s_add_i32 s12, s12, s60
	global_load_lds_dwordx4 v[232:233], off
	v_lshl_add_u64 v[234:235], s[10:11], 0, v[0:1]
	s_mov_b32 m0, s12
	v_lshl_add_u64 v[236:237], s[26:27], 0, v[142:143]
	global_load_lds_dwordx4 v[234:235], off
	v_lshl_add_u64 v[234:235], s[10:11], 0, v[142:143]
	s_add_i32 m0, s12, 0x2000
	s_nop 0
	global_load_lds_dwordx4 v[234:235], off
	v_lshl_add_u64 v[234:235], s[26:27], 0, v[0:1]
	s_mov_b32 m0, s61
	s_nop 0
	global_load_lds_dwordx4 v[234:235], off
	s_mov_b32 m0, s62
	s_nop 0
	global_load_lds_dwordx4 v[236:237], off
	s_waitcnt vmcnt(8) lgkmcnt(0)
	s_barrier
; #define PG8_STAGE(bufoff, gbase, voff) do { _Pragma("unroll") for (int _i = 0; _i < 2; ++_i) \
;         __builtin_amdgcn_global_load_lds((const unsigned*)((const char*)(gbase) + (voff)[_i]), (PG8_LAS unsigned*)(lds + (bufoff) + ldsw + _i * 8192), 16, 0, 0); } while (0)
; #define PG8_LDA(dst, b, h) do { _Pragma("unroll") for (int m = 0; m < 4; ++m) _Pragma("unroll") for (int k = 0; k < 2; ++k) dst[m][k] = *(const PG8_LAS bf16x8*)(lds + PG8_SA(b, h) + aoff + m * 2048 + k * 1024); } while (0)
; #define PG8_LDB(dst, b, h) do { _Pragma("unroll") for (int n = 0; n < 2; ++n) _Pragma("unroll") for (int k = 0; k < 2; ++k) dst[n][k] = *(const PG8_LAS bf16x8*)(lds + PG8_SB(b, h) + boff + n * 2048 + k * 1024); } while (0)
; #define PG8_MMA(ai, bj, At, Bt) do { __builtin_amdgcn_s_setprio(1); _Pragma("unroll") for (int m = 0; m < 4; ++m) _Pragma("unroll") for (int n = 0; n < 2; ++n) _Pragma("unroll") for (int k = 0; k < 2; ++k) \
;         acc[ai][bj][m][n] = __builtin_amdgcn_mfma_f32_16x16x32_bf16(Bt[n][k], At[m][k], acc[ai][bj][m][n], 0, 0, 0); __builtin_amdgcn_s_setprio(0); } while (0)
; #define PG8_WAIT_V(n) asm volatile("s_waitcnt vmcnt(" #n ")" ::: "memory")
; #define PG8_WAIT_L(n) asm volatile("s_waitcnt lgkmcnt(" #n ")" ::: "memory")
; #define PG8_BAR __builtin_amdgcn_s_barrier()
; #define PG8_SCHED __builtin_amdgcn_sched_barrier(0)
; template <class Epi, class Sched, bool ALIGN_EPI = false, bool SP2 = false>
; __device__ __forceinline__ void gemm_phase(PG8_LAS unsigned char* lds, const Gemm g, const Sched& S, const Epi& E) {
;     ...
;             PG8_WAIT_V(8); PG8_WAIT_L(0); PG8_BAR; PG8_MMA(1, 0, At, B0); PG8_MMA(1, 1, At, B1); PG8_BAR; PG8_SCHED;
;             PG8_LDB(B0, 1, 0); PG8_LDB(B1, 1, 1); PG8_SCHED; PG8_LDA(At, 1, 0); PG8_STAGE(PG8_SA(0, 1), a2 + hstep, voffA);
;             PG8_WAIT_V(8); PG8_WAIT_L(0); PG8_BAR; PG8_MMA(0, 0, At, B0); PG8_MMA(0, 1, At, B1); PG8_BAR; PG8_SCHED;
;             PG8_LDA(At, 1, 1); PG8_STAGE(PG8_SB(1, 0), b3, voffB); PG8_STAGE(PG8_SB(1, 1), b3 + hstep, voffB); PG8_STAGE(PG8_SA(1, 0), a3, voffA);
;             PG8_WAIT_V(8); PG8_WAIT_L(0); PG8_BAR; PG8_MMA(1, 0, At, B0); PG8_MMA(1, 1, At, B1); PG8_BAR; PG8_SCHED;
	v_mfma_f32_16x16x32_bf16 v[62:65], v[148:151], v[180:183], v[62:65]
	v_mfma_f32_16x16x32_bf16 v[58:61], v[156:159], v[180:183], v[58:61]
	v_mfma_f32_16x16x32_bf16 v[46:49], v[148:151], v[194:197], v[46:49]
	v_mfma_f32_16x16x32_bf16 v[42:45], v[156:159], v[194:197], v[42:45]
	v_mfma_f32_16x16x32_bf16 v[30:33], v[148:151], v[216:219], v[30:33]
	v_mfma_f32_16x16x32_bf16 v[26:29], v[156:159], v[216:219], v[26:29]
	v_mfma_f32_16x16x32_bf16 v[14:17], v[148:151], v[224:227], v[14:17]
	v_mfma_f32_16x16x32_bf16 v[10:13], v[156:159], v[224:227], v[10:13]
	v_mfma_f32_16x16x32_bf16 v[62:65], v[152:155], v[190:193], v[62:65]
	v_mfma_f32_16x16x32_bf16 v[58:61], v[160:163], v[190:193], v[58:61]
	v_mfma_f32_16x16x32_bf16 v[46:49], v[152:155], v[198:201], v[46:49]
	v_mfma_f32_16x16x32_bf16 v[42:45], v[160:163], v[198:201], v[42:45]
	v_mfma_f32_16x16x32_bf16 v[30:33], v[152:155], v[220:223], v[30:33]
	v_mfma_f32_16x16x32_bf16 v[26:29], v[160:163], v[220:223], v[26:29]
	v_mfma_f32_16x16x32_bf16 v[14:17], v[152:155], v[228:231], v[14:17]
	v_mfma_f32_16x16x32_bf16 v[10:13], v[160:163], v[228:231], v[10:13]
	v_mfma_f32_16x16x32_bf16 v[54:57], v[164:167], v[180:183], v[54:57]
	v_mfma_f32_16x16x32_bf16 v[50:53], v[172:175], v[180:183], v[50:53]
	v_mfma_f32_16x16x32_bf16 v[38:41], v[164:167], v[194:197], v[38:41]
	v_mfma_f32_16x16x32_bf16 v[34:37], v[172:175], v[194:197], v[34:37]
	v_mfma_f32_16x16x32_bf16 v[22:25], v[164:167], v[216:219], v[22:25]
	v_mfma_f32_16x16x32_bf16 v[18:21], v[172:175], v[216:219], v[18:21]
	v_mfma_f32_16x16x32_bf16 v[6:9], v[164:167], v[224:227], v[6:9]
	v_mfma_f32_16x16x32_bf16 v[2:5], v[172:175], v[224:227], v[2:5]
	v_mfma_f32_16x16x32_bf16 v[54:57], v[168:171], v[190:193], v[54:57]
	v_mfma_f32_16x16x32_bf16 v[50:53], v[176:179], v[190:193], v[50:53]
	v_mfma_f32_16x16x32_bf16 v[38:41], v[168:171], v[198:201], v[38:41]
	v_mfma_f32_16x16x32_bf16 v[34:37], v[176:179], v[198:201], v[34:37]
	v_mfma_f32_16x16x32_bf16 v[22:25], v[168:171], v[220:223], v[22:25]
	v_mfma_f32_16x16x32_bf16 v[18:21], v[176:179], v[220:223], v[18:21]
	v_mfma_f32_16x16x32_bf16 v[6:9], v[168:171], v[228:231], v[6:9]
	v_mfma_f32_16x16x32_bf16 v[2:5], v[176:179], v[228:231], v[2:5]
	s_barrier
	s_add_i32 s12, 0, 0x18000
	s_add_i32 s13, 0, 0x1c000
	v_add_u32_e32 v160, s12, v187
	v_add_u32_e32 v176, s13, v187
	ds_read_b128 v[148:151], v160
	ds_read_b128 v[152:155], v160 offset:1024
	ds_read_b128 v[156:159], v160 offset:2048
	ds_read_b128 v[160:163], v160 offset:3072
	ds_read_b128 v[164:167], v176
	ds_read_b128 v[168:171], v176 offset:1024
	ds_read_b128 v[172:175], v176 offset:2048
	ds_read_b128 v[176:179], v176 offset:3072
	s_add_u32 s10, s26, 0x80000
	s_addc_u32 s11, s27, 0
	s_mov_b32 m0, s63
	v_lshl_add_u64 v[238:239], s[10:11], 0, v[0:1]
	ds_read_b128 v[180:183], v189 offset:32768
	ds_read_b128 v[190:193], v189 offset:33792
	ds_read_b128 v[194:197], v189 offset:34816
	ds_read_b128 v[198:201], v189 offset:35840
	ds_read_b128 v[216:219], v189 offset:36864
	ds_read_b128 v[220:223], v189 offset:37888
	ds_read_b128 v[224:227], v189 offset:38912
	ds_read_b128 v[228:231], v189 offset:39936
	global_load_lds_dwordx4 v[238:239], off
	v_lshl_add_u64 v[238:239], s[10:11], 0, v[142:143]
	s_mov_b32 m0, s64
	s_nop 0
	global_load_lds_dwordx4 v[238:239], off
	s_waitcnt vmcnt(8) lgkmcnt(0)
	s_barrier
	v_mfma_f32_16x16x32_bf16 v[126:129], v[148:151], v[180:183], v[126:129]
	v_mfma_f32_16x16x32_bf16 v[122:125], v[156:159], v[180:183], v[122:125]
	v_mfma_f32_16x16x32_bf16 v[110:113], v[148:151], v[194:197], v[110:113]
	v_mfma_f32_16x16x32_bf16 v[106:109], v[156:159], v[194:197], v[106:109]
	v_mfma_f32_16x16x32_bf16 v[94:97], v[148:151], v[216:219], v[94:97]
	v_mfma_f32_16x16x32_bf16 v[90:93], v[156:159], v[216:219], v[90:93]
	v_mfma_f32_16x16x32_bf16 v[78:81], v[148:151], v[224:227], v[78:81]
	v_mfma_f32_16x16x32_bf16 v[74:77], v[156:159], v[224:227], v[74:77]
	v_mfma_f32_16x16x32_bf16 v[126:129], v[152:155], v[190:193], v[126:129]
	v_mfma_f32_16x16x32_bf16 v[122:125], v[160:163], v[190:193], v[122:125]
	v_mfma_f32_16x16x32_bf16 v[110:113], v[152:155], v[198:201], v[110:113]
	v_mfma_f32_16x16x32_bf16 v[106:109], v[160:163], v[198:201], v[106:109]
	v_mfma_f32_16x16x32_bf16 v[94:97], v[152:155], v[220:223], v[94:97]
	v_mfma_f32_16x16x32_bf16 v[90:93], v[160:163], v[220:223], v[90:93]
	v_mfma_f32_16x16x32_bf16 v[78:81], v[152:155], v[228:231], v[78:81]
	v_mfma_f32_16x16x32_bf16 v[74:77], v[160:163], v[228:231], v[74:77]
	v_mfma_f32_16x16x32_bf16 v[118:121], v[164:167], v[180:183], v[118:121]
	v_mfma_f32_16x16x32_bf16 v[114:117], v[172:175], v[180:183], v[114:117]
	v_mfma_f32_16x16x32_bf16 v[102:105], v[164:167], v[194:197], v[102:105]
	v_mfma_f32_16x16x32_bf16 v[98:101], v[172:175], v[194:197], v[98:101]
	v_mfma_f32_16x16x32_bf16 v[86:89], v[164:167], v[216:219], v[86:89]
	v_mfma_f32_16x16x32_bf16 v[82:85], v[172:175], v[216:219], v[82:85]
	v_mfma_f32_16x16x32_bf16 v[70:73], v[164:167], v[224:227], v[70:73]
	v_mfma_f32_16x16x32_bf16 v[66:69], v[172:175], v[224:227], v[66:69]
	v_mfma_f32_16x16x32_bf16 v[118:121], v[168:171], v[190:193], v[118:121]
	v_mfma_f32_16x16x32_bf16 v[114:117], v[176:179], v[190:193], v[114:117]
	v_mfma_f32_16x16x32_bf16 v[102:105], v[168:171], v[198:201], v[102:105]
	v_mfma_f32_16x16x32_bf16 v[98:101], v[176:179], v[198:201], v[98:101]
	v_mfma_f32_16x16x32_bf16 v[86:89], v[168:171], v[220:223], v[86:89]
	v_mfma_f32_16x16x32_bf16 v[82:85], v[176:179], v[220:223], v[82:85]
	v_mfma_f32_16x16x32_bf16 v[70:73], v[168:171], v[228:231], v[70:73]
	v_mfma_f32_16x16x32_bf16 v[66:69], v[176:179], v[228:231], v[66:69]
	s_barrier
; #define PG8_STAGE(bufoff, gbase, voff) do { _Pragma("unroll") for (int _i = 0; _i < 2; ++_i) \
;         __builtin_amdgcn_global_load_lds((const unsigned*)((const char*)(gbase) + (voff)[_i]), (PG8_LAS unsigned*)(lds + (bufoff) + ldsw + _i * 8192), 16, 0, 0); } while (0)
; #define PG8_LDA(dst, b, h) do { _Pragma("unroll") for (int m = 0; m < 4; ++m) _Pragma("unroll") for (int k = 0; k < 2; ++k) dst[m][k] = *(const PG8_LAS bf16x8*)(lds + PG8_SA(b, h) + aoff + m * 2048 + k * 1024); } while (0)
; #define PG8_LDB(dst, b, h) do { _Pragma("unroll") for (int n = 0; n < 2; ++n) _Pragma("unroll") for (int k = 0; k < 2; ++k) dst[n][k] = *(const PG8_LAS bf16x8*)(lds + PG8_SB(b, h) + boff + n * 2048 + k * 1024); } while (0)
; template <class Epi, class Sched, bool ALIGN_EPI = false, bool SP2 = false>
; __device__ __forceinline__ void gemm_phase(PG8_LAS unsigned char* lds, const Gemm g, const Sched& S, const Epi& E) {
;     ...
;         for (int t = 0; t < nt; t += 2) {
;             const bool last = (t == nt - 2);
;             const char* a1 = cA + (size_t)(t + 1) * kstep;
;             const char* a2 = last ? nA : cA + (size_t)(t + 2) * kstep; const char* b2 = last ? nB : cB + (size_t)(t + 2) * kstep;
;             const char* a3 = a2 + kstep; const char* b3 = b2 + kstep;
;             if (last && has_next) S.a_ready(nxt);
;             if constexpr (SP2) {
;             PG8_LDB(B0, 0, 0); PG8_LDB(B1, 0, 1); PG8_SCHED; PG8_LDA(At, 0, 0); PG8_STAGE(PG8_SA(1, 1), a1 + hstep, voffA);
;             PG8_WAIT_V(8); PG8_WAIT_L(0); PG8_BAR; PG8_MMA(0, 0, At, B0); PG8_MMA(0, 1, At, B1); PG8_BAR; PG8_SCHED;
;             PG8_LDA(At, 0, 1); PG8_STAGE(PG8_SB(0, 0), b2, voffB); PG8_STAGE(PG8_SB(0, 1), b2 + hstep, voffB); PG8_STAGE(PG8_SA(0, 0), a2, voffA);
;             PG8_WAIT_V(8); PG8_WAIT_L(0); PG8_BAR; PG8_MMA(1, 0, At, B0); PG8_MMA(1, 1, At, B1); PG8_BAR; PG8_SCHED;
;             PG8_LDB(B0, 1, 0); PG8_LDB(B1, 1, 1); PG8_SCHED; PG8_LDA(At, 1, 0); PG8_STAGE(PG8_SA(0, 1), a2 + hstep, voffA);
;             PG8_WAIT_V(8); PG8_WAIT_L(0); PG8_BAR; PG8_MMA(0, 0, At, B0); PG8_MMA(0, 1, At, B1); PG8_BAR; PG8_SCHED;
;             PG8_LDA(At, 1, 1); PG8_STAGE(PG8_SB(1, 0), b3, voffB); PG8_STAGE(PG8_SB(1, 1), b3 + hstep, voffB); PG8_STAGE(PG8_SA(1, 0), a3, voffA);
;             PG8_WAIT_V(8); PG8_WAIT_L(0); PG8_BAR; PG8_MMA(1, 0, At, B0); PG8_MMA(1, 1, At, B1); PG8_BAR; PG8_SCHED;
	s_add_i32 s10, s12, s60
	v_lshl_add_u64 v[184:185], v[184:185], 0, s[30:31]
	s_mov_b32 m0, s10
	ds_read_b128 v[180:183], v189 offset:49152
	ds_read_b128 v[190:193], v189 offset:50176
	ds_read_b128 v[194:197], v189 offset:51200
	ds_read_b128 v[198:201], v189 offset:52224
	ds_read_b128 v[216:219], v189 offset:53248
	ds_read_b128 v[220:223], v189 offset:54272
	ds_read_b128 v[224:227], v189 offset:55296
	ds_read_b128 v[228:231], v189 offset:56320
	global_load_lds_dwordx4 v[184:185], off
	s_add_i32 m0, s10, 0x2000
	s_add_u32 s10, s24, 0x80080
	v_lshl_add_u64 v[184:185], v[232:233], 0, s[30:31]
	s_addc_u32 s11, s25, 0
	s_add_i32 s12, s13, s60
	global_load_lds_dwordx4 v[184:185], off
	v_lshl_add_u64 v[184:185], s[10:11], 0, v[0:1]
	s_mov_b32 m0, s12
	s_nop 0
	global_load_lds_dwordx4 v[184:185], off
	v_lshl_add_u64 v[184:185], s[10:11], 0, v[142:143]
	s_add_i32 m0, s12, 0x2000
	s_nop 0
	global_load_lds_dwordx4 v[184:185], off
	v_lshl_add_u64 v[184:185], v[234:235], 0, s[30:31]
	s_mov_b32 m0, s65
	s_nop 0
	global_load_lds_dwordx4 v[184:185], off
	v_lshl_add_u64 v[184:185], v[236:237], 0, s[30:31]
	s_mov_b32 m0, s66
	s_nop 0
	global_load_lds_dwordx4 v[184:185], off
	s_waitcnt vmcnt(8) lgkmcnt(0)
	s_barrier
	v_mfma_f32_16x16x32_bf16 v[62:65], v[148:151], v[180:183], v[62:65]
	v_mfma_f32_16x16x32_bf16 v[58:61], v[156:159], v[180:183], v[58:61]
	v_mfma_f32_16x16x32_bf16 v[46:49], v[148:151], v[194:197], v[46:49]
	v_mfma_f32_16x16x32_bf16 v[42:45], v[156:159], v[194:197], v[42:45]
	v_mfma_f32_16x16x32_bf16 v[30:33], v[148:151], v[216:219], v[30:33]
	v_mfma_f32_16x16x32_bf16 v[26:29], v[156:159], v[216:219], v[26:29]
	v_mfma_f32_16x16x32_bf16 v[14:17], v[148:151], v[224:227], v[14:17]
	v_mfma_f32_16x16x32_bf16 v[10:13], v[156:159], v[224:227], v[10:13]
	v_mfma_f32_16x16x32_bf16 v[62:65], v[152:155], v[190:193], v[62:65]
	v_mfma_f32_16x16x32_bf16 v[58:61], v[160:163], v[190:193], v[58:61]
	v_mfma_f32_16x16x32_bf16 v[46:49], v[152:155], v[198:201], v[46:49]
	v_mfma_f32_16x16x32_bf16 v[42:45], v[160:163], v[198:201], v[42:45]
	v_mfma_f32_16x16x32_bf16 v[30:33], v[152:155], v[220:223], v[30:33]
	v_mfma_f32_16x16x32_bf16 v[26:29], v[160:163], v[220:223], v[26:29]
	v_mfma_f32_16x16x32_bf16 v[14:17], v[152:155], v[228:231], v[14:17]
	v_mfma_f32_16x16x32_bf16 v[10:13], v[160:163], v[228:231], v[10:13]
	v_mfma_f32_16x16x32_bf16 v[54:57], v[164:167], v[180:183], v[54:57]
	v_mfma_f32_16x16x32_bf16 v[50:53], v[172:175], v[180:183], v[50:53]
	v_mfma_f32_16x16x32_bf16 v[38:41], v[164:167], v[194:197], v[38:41]
	v_mfma_f32_16x16x32_bf16 v[34:37], v[172:175], v[194:197], v[34:37]
	v_mfma_f32_16x16x32_bf16 v[22:25], v[164:167], v[216:219], v[22:25]
	v_mfma_f32_16x16x32_bf16 v[18:21], v[172:175], v[216:219], v[18:21]
	v_mfma_f32_16x16x32_bf16 v[6:9], v[164:167], v[224:227], v[6:9]
	v_mfma_f32_16x16x32_bf16 v[2:5], v[172:175], v[224:227], v[2:5]
	v_mfma_f32_16x16x32_bf16 v[54:57], v[168:171], v[190:193], v[54:57]
	v_mfma_f32_16x16x32_bf16 v[50:53], v[176:179], v[190:193], v[50:53]
	v_mfma_f32_16x16x32_bf16 v[38:41], v[168:171], v[198:201], v[38:41]
	v_mfma_f32_16x16x32_bf16 v[34:37], v[176:179], v[198:201], v[34:37]
	v_mfma_f32_16x16x32_bf16 v[22:25], v[168:171], v[220:223], v[22:25]
	v_mfma_f32_16x16x32_bf16 v[18:21], v[176:179], v[220:223], v[18:21]
	v_mfma_f32_16x16x32_bf16 v[6:9], v[168:171], v[228:231], v[6:9]
	v_mfma_f32_16x16x32_bf16 v[2:5], v[176:179], v[228:231], v[2:5]
	s_barrier
	s_add_i32 s22, s22, 2
	s_add_u32 s14, s14, 0x100
	s_addc_u32 s15, s15, 0
	s_cmp_gt_u32 s22, 29
	s_mov_b64 s[16:17], s[18:19]
	s_cbranch_scc0 .LBB0_601
; __device__ __forceinline__ unsigned cvt_pk_bf16(float lo, float hi) { unsigned r; asm volatile("v_cvt_pk_bf16_f32 %0, %1, %2" : "=v"(r) : "v"(lo), "v"(hi)); return r; }
;     __device__ __forceinline__ void operator()(const f32x4 (&acc)[2][2][4][2], const Unit& u, int wr, int wc, int fr, int fq) const {
;     ...
;         for (int ai = 0; ai < 2; ++ai) {
;             u32x2 bv[4][2][2];
; #pragma unroll
;             for (int m = 0; m < 4; ++m) { const size_t off = (size_t)(row0 + ai * HALF + m * 16) * ldc + col0;
; #pragma unroll
;                 for (int bj = 0; bj < 2; ++bj)
; #pragma unroll
;                     for (int n = 0; n < 2; ++n) bv[m][bj][n] = *(const u32x2*)(xb + off + bj * HALF + n * 16); }
;             asm volatile("" ::: "memory");
; #pragma unroll
;             for (int m = 0; m < 4; ++m) {
;                 const int row = row0 + ai * HALF + m * 16;
;                 const size_t off = (size_t)row * ldc + col0;
;                 float s = 0.f;
; #pragma unroll
;                 for (int bj = 0; bj < 2; ++bj)
; #pragma unroll
;                     for (int n = 0; n < 2; ++n) {
;                         const size_t c = off + bj * HALF + n * 16;
;                         const u32x2 w0 = bv[m][bj][n];
;                         const f32x4 b = {__uint_as_float(w0.x << 16), __uint_as_float(w0.x & 0xffff0000u), __uint_as_float(w0.y << 16), __uint_as_float(w0.y & 0xffff0000u)};
;                         const f32x4 o = b + acc[ai][bj][m][n];
;                         if (fin) { *(f32x4*)(outf + c) = o; }
;                         else { u32x2 w; w.x = cvt_pk_bf16(o[0], o[1]); w.y = cvt_pk_bf16(o[2], o[3]); *(u32x2*)(xb + c) = w;
;                                s += (o[0] * o[0] + o[1] * o[1]) + (o[2] * o[2] + o[3] * o[3]); }
;                     }
;                 if (!fin) { s += __shfl_xor(s, 16); s += __shfl_xor(s, 32); if (fq == 0) unsafeAtomicAdd(ssq + row, s); }
	v_lshl_or_b32 v148, s2, 8, v188
	v_lshl_add_u32 v152, s4, 8, v186
	v_ashrrev_i32_e32 v149, 31, v148
	v_lshlrev_b64 v[190:191], 1, v[148:149]
	v_ashrrev_i32_e32 v153, 31, v152
	v_lshl_add_u64 v[150:151], s[48:49], 0, v[190:191]
	v_lshlrev_b64 v[154:155], 12, v[152:153]
	v_lshl_add_u64 v[156:157], v[150:151], 0, v[154:155]
	global_load_dwordx2 v[192:193], v[156:157], off
	global_load_dwordx2 v[194:195], v[156:157], off offset:32
	global_load_dwordx2 v[196:197], v[156:157], off offset:256
	global_load_dwordx2 v[198:199], v[156:157], off offset:288
	v_or_b32_e32 v184, 16, v152
	v_ashrrev_i32_e32 v185, 31, v184
	v_lshlrev_b64 v[156:157], 12, v[184:185]
	v_or_b32_e32 v174, 32, v152
	v_lshl_add_u64 v[156:157], v[150:151], 0, v[156:157]
	v_ashrrev_i32_e32 v175, 31, v174
	global_load_dwordx2 v[182:183], v[156:157], off
	global_load_dwordx2 v[180:181], v[156:157], off offset:32
	global_load_dwordx2 v[178:179], v[156:157], off offset:256
	global_load_dwordx2 v[176:177], v[156:157], off offset:288
	v_lshlrev_b64 v[156:157], 12, v[174:175]
	v_or_b32_e32 v158, 48, v152
	v_lshl_add_u64 v[156:157], v[150:151], 0, v[156:157]
	v_ashrrev_i32_e32 v159, 31, v158
	global_load_dwordx2 v[172:173], v[156:157], off
	global_load_dwordx2 v[170:171], v[156:157], off offset:32
	global_load_dwordx2 v[166:167], v[156:157], off offset:256
	global_load_dwordx2 v[162:163], v[156:157], off offset:288
	v_lshlrev_b64 v[156:157], 12, v[158:159]
	v_lshl_add_u64 v[156:157], v[150:151], 0, v[156:157]
	global_load_dwordx2 v[168:169], v[156:157], off
	global_load_dwordx2 v[164:165], v[156:157], off offset:32
	global_load_dwordx2 v[160:161], v[156:157], off offset:256
	s_nop 0
	global_load_dwordx2 v[156:157], v[156:157], off offset:288
	s_waitcnt vmcnt(0)
	v_lshlrev_b32_e32 v200, 16, v192
	v_and_b32_e32 v201, 0xffff0000, v192
	v_lshlrev_b32_e32 v192, 16, v193
	v_and_b32_e32 v193, 0xffff0000, v193
	v_pk_add_f32 v[126:127], v[126:127], v[200:201]
	v_pk_add_f32 v[128:129], v[128:129], v[192:193]
	v_cvt_pk_bf16_f32 v192, v126, v127
	v_mul_f32_e32 v127, v127, v127
	v_lshl_add_u64 v[200:201], s[48:49], 0, v[154:155]
	v_fmac_f32_e32 v127, v126, v126
	v_mul_f32_e32 v126, v129, v129
	v_lshl_add_u64 v[190:191], v[200:201], 0, v[190:191]
	v_fmac_f32_e32 v126, v128, v128
	v_cvt_pk_bf16_f32 v193, v128, v129
	global_store_dwordx2 v[190:191], v[192:193], off
	v_add_f32_e32 v192, v127, v126
	v_lshlrev_b32_e32 v126, 16, v194
	v_and_b32_e32 v127, 0xffff0000, v194
	v_lshlrev_b32_e32 v128, 16, v195
	v_and_b32_e32 v129, 0xffff0000, v195
	v_pk_add_f32 v[122:123], v[122:123], v[126:127]
	v_pk_add_f32 v[124:125], v[124:125], v[128:129]
	v_cvt_pk_bf16_f32 v126, v122, v123
	v_mul_f32_e32 v123, v123, v123
	v_fmac_f32_e32 v123, v122, v122
	v_mul_f32_e32 v122, v125, v125
	v_fmac_f32_e32 v122, v124, v124
	v_add_f32_e32 v122, v123, v122
	v_cvt_pk_bf16_f32 v127, v124, v125
	global_store_dwordx2 v[190:191], v[126:127], off offset:32
	v_add_f32_e32 v126, v192, v122
	v_lshlrev_b32_e32 v122, 16, v196
	v_and_b32_e32 v123, 0xffff0000, v196
	v_lshlrev_b32_e32 v124, 16, v197
	v_and_b32_e32 v125, 0xffff0000, v197
	v_pk_add_f32 v[118:119], v[118:119], v[122:123]
	v_pk_add_f32 v[120:121], v[120:121], v[124:125]
	v_cvt_pk_bf16_f32 v122, v118, v119
	v_mul_f32_e32 v119, v119, v119
	v_fmac_f32_e32 v119, v118, v118
	v_mul_f32_e32 v118, v121, v121
	v_fmac_f32_e32 v118, v120, v120
	v_add_f32_e32 v118, v119, v118
	v_cvt_pk_bf16_f32 v123, v120, v121
	global_store_dwordx2 v[190:191], v[122:123], off offset:256
	v_add_f32_e32 v122, v126, v118
	v_lshlrev_b32_e32 v118, 16, v198
	v_and_b32_e32 v119, 0xffff0000, v198
	v_lshlrev_b32_e32 v120, 16, v199
	v_and_b32_e32 v121, 0xffff0000, v199
	v_pk_add_f32 v[114:115], v[114:115], v[118:119]
	v_pk_add_f32 v[116:117], v[116:117], v[120:121]
	v_cvt_pk_bf16_f32 v118, v114, v115
	v_mul_f32_e32 v115, v115, v115
	v_fmac_f32_e32 v115, v114, v114
	v_mul_f32_e32 v114, v117, v117
	v_cvt_pk_bf16_f32 v119, v116, v117
	v_fmac_f32_e32 v114, v116, v116
	v_and_b32_e32 v116, 64, v208
	v_add_f32_e32 v114, v115, v114
	v_xor_b32_e32 v115, 16, v208
	v_add_u32_e32 v117, 64, v116
	v_cmp_lt_i32_e32 vcc, v115, v117
	v_add_f32_e32 v114, v122, v114
	global_store_dwordx2 v[190:191], v[118:119], off offset:288
	v_cndmask_b32_e32 v115, v208, v115, vcc
	v_lshlrev_b32_e32 v116, 2, v115
	ds_bpermute_b32 v115, v116, v114
	s_waitcnt lgkmcnt(0)
	v_add_f32_e32 v118, v114, v115
	v_xor_b32_e32 v114, 32, v208
	v_cmp_lt_i32_e32 vcc, v114, v117
	s_nop 1
	v_cndmask_b32_e32 v114, v208, v114, vcc
	v_lshlrev_b32_e32 v117, 2, v114
	ds_bpermute_b32 v119, v117, v118
	v_lshl_add_u64 v[114:115], v[152:153], 2, s[50:51]
	s_and_saveexec_b64 s[16:17], s[42:43]
	s_cbranch_execz .LBB0_604
	s_waitcnt lgkmcnt(0)
	v_add_f32_e32 v118, v118, v119
	global_atomic_add_f32 v[114:115], v118, off

; #define PG8_STAGE(bufoff, gbase, voff) do { _Pragma("unroll") for (int _i = 0; _i < 2; ++_i) \
;         __builtin_amdgcn_global_load_lds((const unsigned*)((const char*)(gbase) + (voff)[_i]), (PG8_LAS unsigned*)(lds + (bufoff) + ldsw + _i * 8192), 16, 0, 0); } while (0)
; #define PG8_LDA(dst, b, h) do { _Pragma("unroll") for (int m = 0; m < 4; ++m) _Pragma("unroll") for (int k = 0; k < 2; ++k) dst[m][k] = *(const PG8_LAS bf16x8*)(lds + PG8_SA(b, h) + aoff + m * 2048 + k * 1024); } while (0)
; #define PG8_LDB(dst, b, h) do { _Pragma("unroll") for (int n = 0; n < 2; ++n) _Pragma("unroll") for (int k = 0; k < 2; ++k) dst[n][k] = *(const PG8_LAS bf16x8*)(lds + PG8_SB(b, h) + boff + n * 2048 + k * 1024); } while (0)
; #define PG8_MMA(ai, bj, At, Bt) do { __builtin_amdgcn_s_setprio(1); _Pragma("unroll") for (int m = 0; m < 4; ++m) _Pragma("unroll") for (int n = 0; n < 2; ++n) _Pragma("unroll") for (int k = 0; k < 2; ++k) \
;         acc[ai][bj][m][n] = __builtin_amdgcn_mfma_f32_16x16x32_bf16(Bt[n][k], At[m][k], acc[ai][bj][m][n], 0, 0, 0); __builtin_amdgcn_s_setprio(0); } while (0)
; #define PG8_WAIT_V(n) asm volatile("s_waitcnt vmcnt(" #n ")" ::: "memory")
; #define PG8_WAIT_L(n) asm volatile("s_waitcnt lgkmcnt(" #n ")" ::: "memory")
; #define PG8_BAR __builtin_amdgcn_s_barrier()
; #define PG8_SCHED __builtin_amdgcn_sched_barrier(0)
; template <class Epi, class Sched, bool ALIGN_EPI = false, bool SP2 = false>
; __device__ __forceinline__ void gemm_phase(PG8_LAS unsigned char* lds, const Gemm g, const Sched& S, const Epi& E) {
;     ...
;             PG8_LDB(B0, 0, 0); PG8_LDB(B1, 0, 1); PG8_SCHED; PG8_LDA(At, 0, 0); PG8_STAGE(PG8_SA(1, 1), a1 + hstep, voffA);
;             PG8_WAIT_V(8); PG8_WAIT_L(0); PG8_BAR; PG8_MMA(0, 0, At, B0); PG8_MMA(0, 1, At, B1); PG8_BAR; PG8_SCHED;
;             PG8_LDA(At, 0, 1); PG8_STAGE(PG8_SB(0, 0), b2, voffB); PG8_STAGE(PG8_SB(0, 1), b2 + hstep, voffB); PG8_STAGE(PG8_SA(0, 0), a2, voffA);
;             PG8_WAIT_V(8); PG8_WAIT_L(0); PG8_BAR; PG8_MMA(1, 0, At, B0); PG8_MMA(1, 1, At, B1); PG8_BAR; PG8_SCHED;
.LBB0_686:
	s_add_u32 s10, s16, 0xfff80080
	s_addc_u32 s11, s17, -1
	s_add_i32 s12, 0, 0x10000
	s_cmp_eq_u32 s22, 28
	s_cselect_b32 s25, s5, s11
	s_cselect_b32 s24, s7, s10
	v_add_u32_e32 v160, s12, v163
	s_cselect_b32 s19, s8, s15
	s_cselect_b32 s18, s9, s14
	s_add_i32 s13, 0, 0x14000
	ds_read_b128 v[152:155], v160
	ds_read_b128 v[156:159], v160 offset:1024
	ds_read_b128 v[166:169], v160 offset:2048
	ds_read_b128 v[170:173], v160 offset:3072
	v_add_u32_e32 v160, s13, v163
	ds_read_b128 v[174:177], v160
	ds_read_b128 v[178:181], v160 offset:1024
	ds_read_b128 v[182:185], v160 offset:2048
	ds_read_b128 v[186:189], v160 offset:3072
	v_lshl_add_u64 v[160:161], s[16:17], 0, v[148:149]
	s_add_i32 m0, s59, 0xc000
	ds_read_b128 v[190:193], v165
	ds_read_b128 v[194:197], v165 offset:1024
	ds_read_b128 v[198:201], v165 offset:2048
	ds_read_b128 v[216:219], v165 offset:3072
	ds_read_b128 v[220:223], v165 offset:4096
	ds_read_b128 v[224:227], v165 offset:5120
	ds_read_b128 v[228:231], v165 offset:6144
	ds_read_b128 v[232:235], v165 offset:7168
	global_load_lds_dwordx4 v[160:161], off
	v_lshl_add_u64 v[160:161], s[16:17], 0, v[150:151]
	s_add_i32 m0, s59, 0xe000
	s_nop 0
	global_load_lds_dwordx4 v[160:161], off
	s_waitcnt vmcnt(8) lgkmcnt(0)
	s_barrier
	v_mfma_f32_16x16x32_bf16 v[126:129], v[152:155], v[190:193], v[126:129]
	v_mfma_f32_16x16x32_bf16 v[122:125], v[166:169], v[190:193], v[122:125]
	v_mfma_f32_16x16x32_bf16 v[110:113], v[152:155], v[198:201], v[110:113]
	v_mfma_f32_16x16x32_bf16 v[106:109], v[166:169], v[198:201], v[106:109]
	v_mfma_f32_16x16x32_bf16 v[94:97], v[152:155], v[220:223], v[94:97]
	v_mfma_f32_16x16x32_bf16 v[90:93], v[166:169], v[220:223], v[90:93]
	v_mfma_f32_16x16x32_bf16 v[78:81], v[152:155], v[228:231], v[78:81]
	v_mfma_f32_16x16x32_bf16 v[74:77], v[166:169], v[228:231], v[74:77]
	v_mfma_f32_16x16x32_bf16 v[126:129], v[156:159], v[194:197], v[126:129]
	v_mfma_f32_16x16x32_bf16 v[122:125], v[170:173], v[194:197], v[122:125]
	v_mfma_f32_16x16x32_bf16 v[110:113], v[156:159], v[216:219], v[110:113]
	v_mfma_f32_16x16x32_bf16 v[106:109], v[170:173], v[216:219], v[106:109]
	v_mfma_f32_16x16x32_bf16 v[94:97], v[156:159], v[224:227], v[94:97]
	v_mfma_f32_16x16x32_bf16 v[90:93], v[170:173], v[224:227], v[90:93]
	v_mfma_f32_16x16x32_bf16 v[78:81], v[156:159], v[232:235], v[78:81]
	v_mfma_f32_16x16x32_bf16 v[74:77], v[170:173], v[232:235], v[74:77]
	v_mfma_f32_16x16x32_bf16 v[118:121], v[174:177], v[190:193], v[118:121]
	v_mfma_f32_16x16x32_bf16 v[114:117], v[182:185], v[190:193], v[114:117]
	v_mfma_f32_16x16x32_bf16 v[102:105], v[174:177], v[198:201], v[102:105]
	v_mfma_f32_16x16x32_bf16 v[98:101], v[182:185], v[198:201], v[98:101]
	v_mfma_f32_16x16x32_bf16 v[86:89], v[174:177], v[220:223], v[86:89]
	v_mfma_f32_16x16x32_bf16 v[82:85], v[182:185], v[220:223], v[82:85]
	v_mfma_f32_16x16x32_bf16 v[70:73], v[174:177], v[228:231], v[70:73]
	v_mfma_f32_16x16x32_bf16 v[66:69], v[182:185], v[228:231], v[66:69]
	v_mfma_f32_16x16x32_bf16 v[118:121], v[178:181], v[194:197], v[118:121]
	v_mfma_f32_16x16x32_bf16 v[114:117], v[186:189], v[194:197], v[114:117]
	v_mfma_f32_16x16x32_bf16 v[102:105], v[178:181], v[216:219], v[102:105]
	v_mfma_f32_16x16x32_bf16 v[98:101], v[186:189], v[216:219], v[98:101]
	v_mfma_f32_16x16x32_bf16 v[86:89], v[178:181], v[224:227], v[86:89]
	v_mfma_f32_16x16x32_bf16 v[82:85], v[186:189], v[224:227], v[82:85]
	v_mfma_f32_16x16x32_bf16 v[70:73], v[178:181], v[232:235], v[70:73]
	v_mfma_f32_16x16x32_bf16 v[66:69], v[186:189], v[232:235], v[66:69]
	s_barrier
	s_add_i32 s10, s12, s58
	v_lshl_add_u64 v[160:161], s[18:19], 0, v[0:1]
	s_mov_b32 m0, s10
	ds_read_b128 v[190:193], v165 offset:16384
	ds_read_b128 v[194:197], v165 offset:17408
	ds_read_b128 v[198:201], v165 offset:18432
	ds_read_b128 v[216:219], v165 offset:19456
	ds_read_b128 v[220:223], v165 offset:20480
	ds_read_b128 v[224:227], v165 offset:21504
	ds_read_b128 v[228:231], v165 offset:22528
	ds_read_b128 v[232:235], v165 offset:23552
	global_load_lds_dwordx4 v[160:161], off
	s_add_i32 m0, s10, 0x2000
	s_add_u32 s10, s18, 0x80000
	v_lshl_add_u64 v[236:237], s[18:19], 0, v[142:143]
	s_addc_u32 s11, s19, 0
	s_add_i32 s12, s13, s58
	global_load_lds_dwordx4 v[236:237], off
	v_lshl_add_u64 v[238:239], s[10:11], 0, v[0:1]
	s_mov_b32 m0, s12
	v_lshl_add_u64 v[240:241], s[24:25], 0, v[144:145]
	global_load_lds_dwordx4 v[238:239], off
	v_lshl_add_u64 v[238:239], s[10:11], 0, v[142:143]
	s_add_i32 m0, s12, 0x2000
	s_nop 0
	global_load_lds_dwordx4 v[238:239], off
	v_lshl_add_u64 v[238:239], s[24:25], 0, v[146:147]
	s_mov_b32 m0, s59
	s_nop 0
	global_load_lds_dwordx4 v[238:239], off
	s_mov_b32 m0, s60
	s_nop 0
	global_load_lds_dwordx4 v[240:241], off
	s_waitcnt vmcnt(8) lgkmcnt(0)
	s_barrier
; #define PG8_STAGE(bufoff, gbase, voff) do { _Pragma("unroll") for (int _i = 0; _i < 2; ++_i) \
;         __builtin_amdgcn_global_load_lds((const unsigned*)((const char*)(gbase) + (voff)[_i]), (PG8_LAS unsigned*)(lds + (bufoff) + ldsw + _i * 8192), 16, 0, 0); } while (0)
; #define PG8_LDA(dst, b, h) do { _Pragma("unroll") for (int m = 0; m < 4; ++m) _Pragma("unroll") for (int k = 0; k < 2; ++k) dst[m][k] = *(const PG8_LAS bf16x8*)(lds + PG8_SA(b, h) + aoff + m * 2048 + k * 1024); } while (0)
; #define PG8_LDB(dst, b, h) do { _Pragma("unroll") for (int n = 0; n < 2; ++n) _Pragma("unroll") for (int k = 0; k < 2; ++k) dst[n][k] = *(const PG8_LAS bf16x8*)(lds + PG8_SB(b, h) + boff + n * 2048 + k * 1024); } while (0)
; #define PG8_MMA(ai, bj, At, Bt) do { __builtin_amdgcn_s_setprio(1); _Pragma("unroll") for (int m = 0; m < 4; ++m) _Pragma("unroll") for (int n = 0; n < 2; ++n) _Pragma("unroll") for (int k = 0; k < 2; ++k) \
;         acc[ai][bj][m][n] = __builtin_amdgcn_mfma_f32_16x16x32_bf16(Bt[n][k], At[m][k], acc[ai][bj][m][n], 0, 0, 0); __builtin_amdgcn_s_setprio(0); } while (0)
; #define PG8_WAIT_V(n) asm volatile("s_waitcnt vmcnt(" #n ")" ::: "memory")
; #define PG8_WAIT_L(n) asm volatile("s_waitcnt lgkmcnt(" #n ")" ::: "memory")
; #define PG8_BAR __builtin_amdgcn_s_barrier()
; #define PG8_SCHED __builtin_amdgcn_sched_barrier(0)
; template <class Epi, class Sched, bool ALIGN_EPI = false, bool SP2 = false>
; __device__ __forceinline__ void gemm_phase(PG8_LAS unsigned char* lds, const Gemm g, const Sched& S, const Epi& E) {
;     ...
;             PG8_WAIT_V(8); PG8_WAIT_L(0); PG8_BAR; PG8_MMA(1, 0, At, B0); PG8_MMA(1, 1, At, B1); PG8_BAR; PG8_SCHED;
;             PG8_LDB(B0, 1, 0); PG8_LDB(B1, 1, 1); PG8_SCHED; PG8_LDA(At, 1, 0); PG8_STAGE(PG8_SA(0, 1), a2 + hstep, voffA);
;             PG8_WAIT_V(8); PG8_WAIT_L(0); PG8_BAR; PG8_MMA(0, 0, At, B0); PG8_MMA(0, 1, At, B1); PG8_BAR; PG8_SCHED;
;             PG8_LDA(At, 1, 1); PG8_STAGE(PG8_SB(1, 0), b3, voffB); PG8_STAGE(PG8_SB(1, 1), b3 + hstep, voffB); PG8_STAGE(PG8_SA(1, 0), a3, voffA);
;             PG8_WAIT_V(8); PG8_WAIT_L(0); PG8_BAR; PG8_MMA(1, 0, At, B0); PG8_MMA(1, 1, At, B1); PG8_BAR; PG8_SCHED;
	v_mfma_f32_16x16x32_bf16 v[62:65], v[152:155], v[190:193], v[62:65]
	v_mfma_f32_16x16x32_bf16 v[58:61], v[166:169], v[190:193], v[58:61]
	v_mfma_f32_16x16x32_bf16 v[46:49], v[152:155], v[198:201], v[46:49]
	v_mfma_f32_16x16x32_bf16 v[42:45], v[166:169], v[198:201], v[42:45]
	v_mfma_f32_16x16x32_bf16 v[30:33], v[152:155], v[220:223], v[30:33]
	v_mfma_f32_16x16x32_bf16 v[26:29], v[166:169], v[220:223], v[26:29]
	v_mfma_f32_16x16x32_bf16 v[14:17], v[152:155], v[228:231], v[14:17]
	v_mfma_f32_16x16x32_bf16 v[10:13], v[166:169], v[228:231], v[10:13]
	v_mfma_f32_16x16x32_bf16 v[62:65], v[156:159], v[194:197], v[62:65]
	v_mfma_f32_16x16x32_bf16 v[58:61], v[170:173], v[194:197], v[58:61]
	v_mfma_f32_16x16x32_bf16 v[46:49], v[156:159], v[216:219], v[46:49]
	v_mfma_f32_16x16x32_bf16 v[42:45], v[170:173], v[216:219], v[42:45]
	v_mfma_f32_16x16x32_bf16 v[30:33], v[156:159], v[224:227], v[30:33]
	v_mfma_f32_16x16x32_bf16 v[26:29], v[170:173], v[224:227], v[26:29]
	v_mfma_f32_16x16x32_bf16 v[14:17], v[156:159], v[232:235], v[14:17]
	v_mfma_f32_16x16x32_bf16 v[10:13], v[170:173], v[232:235], v[10:13]
	v_mfma_f32_16x16x32_bf16 v[54:57], v[174:177], v[190:193], v[54:57]
	v_mfma_f32_16x16x32_bf16 v[50:53], v[182:185], v[190:193], v[50:53]
	v_mfma_f32_16x16x32_bf16 v[38:41], v[174:177], v[198:201], v[38:41]
	v_mfma_f32_16x16x32_bf16 v[34:37], v[182:185], v[198:201], v[34:37]
	v_mfma_f32_16x16x32_bf16 v[22:25], v[174:177], v[220:223], v[22:25]
	v_mfma_f32_16x16x32_bf16 v[18:21], v[182:185], v[220:223], v[18:21]
	v_mfma_f32_16x16x32_bf16 v[6:9], v[174:177], v[228:231], v[6:9]
	v_mfma_f32_16x16x32_bf16 v[2:5], v[182:185], v[228:231], v[2:5]
	v_mfma_f32_16x16x32_bf16 v[54:57], v[178:181], v[194:197], v[54:57]
	v_mfma_f32_16x16x32_bf16 v[50:53], v[186:189], v[194:197], v[50:53]
	v_mfma_f32_16x16x32_bf16 v[38:41], v[178:181], v[216:219], v[38:41]
	v_mfma_f32_16x16x32_bf16 v[34:37], v[186:189], v[216:219], v[34:37]
	v_mfma_f32_16x16x32_bf16 v[22:25], v[178:181], v[224:227], v[22:25]
	v_mfma_f32_16x16x32_bf16 v[18:21], v[186:189], v[224:227], v[18:21]
	v_mfma_f32_16x16x32_bf16 v[6:9], v[178:181], v[232:235], v[6:9]
	v_mfma_f32_16x16x32_bf16 v[2:5], v[186:189], v[232:235], v[2:5]
	s_barrier
	s_add_i32 s12, 0, 0x18000
	s_add_i32 s13, 0, 0x1c000
	v_add_u32_e32 v170, s12, v163
	v_add_u32_e32 v186, s13, v163
	ds_read_b128 v[152:155], v170
	ds_read_b128 v[156:159], v170 offset:1024
	ds_read_b128 v[166:169], v170 offset:2048
	ds_read_b128 v[170:173], v170 offset:3072
	ds_read_b128 v[174:177], v186
	ds_read_b128 v[178:181], v186 offset:1024
	ds_read_b128 v[182:185], v186 offset:2048
	ds_read_b128 v[186:189], v186 offset:3072
	s_add_u32 s10, s24, 0x80000
	s_addc_u32 s11, s25, 0
	s_mov_b32 m0, s61
	v_lshl_add_u64 v[242:243], s[10:11], 0, v[146:147]
	ds_read_b128 v[190:193], v165 offset:32768
	ds_read_b128 v[194:197], v165 offset:33792
	ds_read_b128 v[198:201], v165 offset:34816
	ds_read_b128 v[216:219], v165 offset:35840
	ds_read_b128 v[220:223], v165 offset:36864
	ds_read_b128 v[224:227], v165 offset:37888
	ds_read_b128 v[228:231], v165 offset:38912
	ds_read_b128 v[232:235], v165 offset:39936
	global_load_lds_dwordx4 v[242:243], off
	v_lshl_add_u64 v[242:243], s[10:11], 0, v[144:145]
	s_mov_b32 m0, s62
	s_nop 0
	global_load_lds_dwordx4 v[242:243], off
	s_waitcnt vmcnt(8) lgkmcnt(0)
	s_barrier
	v_mfma_f32_16x16x32_bf16 v[126:129], v[152:155], v[190:193], v[126:129]
	v_mfma_f32_16x16x32_bf16 v[122:125], v[166:169], v[190:193], v[122:125]
	v_mfma_f32_16x16x32_bf16 v[110:113], v[152:155], v[198:201], v[110:113]
	v_mfma_f32_16x16x32_bf16 v[106:109], v[166:169], v[198:201], v[106:109]
	v_mfma_f32_16x16x32_bf16 v[94:97], v[152:155], v[220:223], v[94:97]
	v_mfma_f32_16x16x32_bf16 v[90:93], v[166:169], v[220:223], v[90:93]
	v_mfma_f32_16x16x32_bf16 v[78:81], v[152:155], v[228:231], v[78:81]
	v_mfma_f32_16x16x32_bf16 v[74:77], v[166:169], v[228:231], v[74:77]
	v_mfma_f32_16x16x32_bf16 v[126:129], v[156:159], v[194:197], v[126:129]
	v_mfma_f32_16x16x32_bf16 v[122:125], v[170:173], v[194:197], v[122:125]
	v_mfma_f32_16x16x32_bf16 v[110:113], v[156:159], v[216:219], v[110:113]
	v_mfma_f32_16x16x32_bf16 v[106:109], v[170:173], v[216:219], v[106:109]
	v_mfma_f32_16x16x32_bf16 v[94:97], v[156:159], v[224:227], v[94:97]
	v_mfma_f32_16x16x32_bf16 v[90:93], v[170:173], v[224:227], v[90:93]
	v_mfma_f32_16x16x32_bf16 v[78:81], v[156:159], v[232:235], v[78:81]
	v_mfma_f32_16x16x32_bf16 v[74:77], v[170:173], v[232:235], v[74:77]
	v_mfma_f32_16x16x32_bf16 v[118:121], v[174:177], v[190:193], v[118:121]
	v_mfma_f32_16x16x32_bf16 v[114:117], v[182:185], v[190:193], v[114:117]
	v_mfma_f32_16x16x32_bf16 v[102:105], v[174:177], v[198:201], v[102:105]
	v_mfma_f32_16x16x32_bf16 v[98:101], v[182:185], v[198:201], v[98:101]
	v_mfma_f32_16x16x32_bf16 v[86:89], v[174:177], v[220:223], v[86:89]
	v_mfma_f32_16x16x32_bf16 v[82:85], v[182:185], v[220:223], v[82:85]
	v_mfma_f32_16x16x32_bf16 v[70:73], v[174:177], v[228:231], v[70:73]
	v_mfma_f32_16x16x32_bf16 v[66:69], v[182:185], v[228:231], v[66:69]
	v_mfma_f32_16x16x32_bf16 v[118:121], v[178:181], v[194:197], v[118:121]
	v_mfma_f32_16x16x32_bf16 v[114:117], v[186:189], v[194:197], v[114:117]
	v_mfma_f32_16x16x32_bf16 v[102:105], v[178:181], v[216:219], v[102:105]
	v_mfma_f32_16x16x32_bf16 v[98:101], v[186:189], v[216:219], v[98:101]
	v_mfma_f32_16x16x32_bf16 v[86:89], v[178:181], v[224:227], v[86:89]
	v_mfma_f32_16x16x32_bf16 v[82:85], v[186:189], v[224:227], v[82:85]
	v_mfma_f32_16x16x32_bf16 v[70:73], v[178:181], v[232:235], v[70:73]
	v_mfma_f32_16x16x32_bf16 v[66:69], v[186:189], v[232:235], v[66:69]
	s_barrier
; #define PG8_STAGE(bufoff, gbase, voff) do { _Pragma("unroll") for (int _i = 0; _i < 2; ++_i) \
;         __builtin_amdgcn_global_load_lds((const unsigned*)((const char*)(gbase) + (voff)[_i]), (PG8_LAS unsigned*)(lds + (bufoff) + ldsw + _i * 8192), 16, 0, 0); } while (0)
; #define PG8_LDA(dst, b, h) do { _Pragma("unroll") for (int m = 0; m < 4; ++m) _Pragma("unroll") for (int k = 0; k < 2; ++k) dst[m][k] = *(const PG8_LAS bf16x8*)(lds + PG8_SA(b, h) + aoff + m * 2048 + k * 1024); } while (0)
; #define PG8_WAIT_V(n) asm volatile("s_waitcnt vmcnt(" #n ")" ::: "memory")
; template <class Epi, class Sched, bool ALIGN_EPI = false, bool SP2 = false>
; __device__ __forceinline__ void gemm_phase(PG8_LAS unsigned char* lds, const Gemm g, const Sched& S, const Epi& E) {
;     ...
;             PG8_LDA(At, 1, 1); PG8_STAGE(PG8_SB(1, 0), b3, voffB); PG8_STAGE(PG8_SB(1, 1), b3 + hstep, voffB); PG8_STAGE(PG8_SA(1, 0), a3, voffA);
;             PG8_WAIT_V(8); PG8_WAIT_L(0); PG8_BAR; PG8_MMA(1, 0, At, B0); PG8_MMA(1, 1, At, B1); PG8_BAR; PG8_SCHED;
;             } else {
;             PG8_LDB(B0, 0, 0); PG8_SCHED; PG8_LDA(At, 0, 0); PG8_STAGE(PG8_SA(1, 1), a1 + hstep, voffA);
;             PG8_WAIT_L(8); PG8_BAR; PG8_WAIT_L(0); PG8_MMA(0, 0, At, B0); PG8_BAR; PG8_SCHED;
;             PG8_LDB(B1, 0, 1); PG8_STAGE(PG8_SB(0, 0), b2, voffB);
;             PG8_BAR; PG8_WAIT_L(0); PG8_MMA(0, 1, At, B1); PG8_BAR;
;             PG8_LDA(At, 0, 1); PG8_STAGE(PG8_SA(0, 0), a2, voffA);
;             PG8_BAR; PG8_WAIT_L(0); PG8_MMA(1, 0, At, B0); PG8_BAR; PG8_SCHED;
;             PG8_STAGE(PG8_SB(0, 1), b2 + hstep, voffB);
;             PG8_WAIT_V(6); PG8_BAR; PG8_MMA(1, 1, At, B1); PG8_BAR;
;             PG8_LDB(B0, 1, 0); PG8_SCHED; PG8_LDA(At, 1, 0); PG8_STAGE(PG8_SA(0, 1), a2 + hstep, voffA);
;             PG8_WAIT_L(8); PG8_BAR; PG8_WAIT_L(0); PG8_MMA(0, 0, At, B0); PG8_BAR; PG8_SCHED;
;             PG8_LDB(B1, 1, 1); PG8_STAGE(PG8_SB(1, 0), b3, voffB);
;             PG8_BAR; PG8_WAIT_L(0); PG8_MMA(0, 1, At, B1); PG8_BAR;
;             PG8_LDA(At, 1, 1); PG8_STAGE(PG8_SA(1, 0), a3, voffA);
;             PG8_BAR; PG8_WAIT_L(0); PG8_MMA(1, 0, At, B0); PG8_BAR; PG8_SCHED;
;             PG8_STAGE(PG8_SB(1, 1), b3 + hstep, voffB);
;             PG8_WAIT_V(6); PG8_BAR; PG8_MMA(1, 1, At, B1); PG8_BAR;
;             }
;         }
;         if constexpr (ALIGN_EPI) { if (wr == 0) PG8_BAR; }
	s_add_i32 s10, s12, s58
	v_lshl_add_u64 v[160:161], v[160:161], 0, s[30:31]
	s_mov_b32 m0, s10
	ds_read_b128 v[190:193], v165 offset:49152
	ds_read_b128 v[194:197], v165 offset:50176
	ds_read_b128 v[198:201], v165 offset:51200
	ds_read_b128 v[216:219], v165 offset:52224
	ds_read_b128 v[220:223], v165 offset:53248
	ds_read_b128 v[224:227], v165 offset:54272
	ds_read_b128 v[228:231], v165 offset:55296
	ds_read_b128 v[232:235], v165 offset:56320
	global_load_lds_dwordx4 v[160:161], off
	s_add_i32 m0, s10, 0x2000
	s_add_u32 s10, s18, 0x80080
	v_lshl_add_u64 v[160:161], v[236:237], 0, s[30:31]
	s_addc_u32 s11, s19, 0
	s_add_i32 s12, s13, s58
	global_load_lds_dwordx4 v[160:161], off
	v_lshl_add_u64 v[160:161], s[10:11], 0, v[0:1]
	s_mov_b32 m0, s12
	s_nop 0
	global_load_lds_dwordx4 v[160:161], off
	v_lshl_add_u64 v[160:161], s[10:11], 0, v[142:143]
	s_add_i32 m0, s12, 0x2000
	s_nop 0
	global_load_lds_dwordx4 v[160:161], off
	v_lshl_add_u64 v[160:161], v[238:239], 0, s[30:31]
	s_mov_b32 m0, s63
	s_nop 0
	global_load_lds_dwordx4 v[160:161], off
	v_lshl_add_u64 v[160:161], v[240:241], 0, s[30:31]
	s_mov_b32 m0, s64
	s_nop 0
	global_load_lds_dwordx4 v[160:161], off
	s_waitcnt vmcnt(8) lgkmcnt(0)
	s_barrier
	v_mfma_f32_16x16x32_bf16 v[62:65], v[152:155], v[190:193], v[62:65]
	v_mfma_f32_16x16x32_bf16 v[58:61], v[166:169], v[190:193], v[58:61]
	v_mfma_f32_16x16x32_bf16 v[46:49], v[152:155], v[198:201], v[46:49]
	v_mfma_f32_16x16x32_bf16 v[42:45], v[166:169], v[198:201], v[42:45]
	v_mfma_f32_16x16x32_bf16 v[30:33], v[152:155], v[220:223], v[30:33]
	v_mfma_f32_16x16x32_bf16 v[26:29], v[166:169], v[220:223], v[26:29]
	v_mfma_f32_16x16x32_bf16 v[14:17], v[152:155], v[228:231], v[14:17]
	v_mfma_f32_16x16x32_bf16 v[10:13], v[166:169], v[228:231], v[10:13]
	v_mfma_f32_16x16x32_bf16 v[62:65], v[156:159], v[194:197], v[62:65]
	v_mfma_f32_16x16x32_bf16 v[58:61], v[170:173], v[194:197], v[58:61]
	v_mfma_f32_16x16x32_bf16 v[46:49], v[156:159], v[216:219], v[46:49]
	v_mfma_f32_16x16x32_bf16 v[42:45], v[170:173], v[216:219], v[42:45]
	v_mfma_f32_16x16x32_bf16 v[30:33], v[156:159], v[224:227], v[30:33]
	v_mfma_f32_16x16x32_bf16 v[26:29], v[170:173], v[224:227], v[26:29]
	v_mfma_f32_16x16x32_bf16 v[14:17], v[156:159], v[232:235], v[14:17]
	v_mfma_f32_16x16x32_bf16 v[10:13], v[170:173], v[232:235], v[10:13]
	v_mfma_f32_16x16x32_bf16 v[54:57], v[174:177], v[190:193], v[54:57]
	v_mfma_f32_16x16x32_bf16 v[50:53], v[182:185], v[190:193], v[50:53]
	v_mfma_f32_16x16x32_bf16 v[38:41], v[174:177], v[198:201], v[38:41]
	v_mfma_f32_16x16x32_bf16 v[34:37], v[182:185], v[198:201], v[34:37]
	v_mfma_f32_16x16x32_bf16 v[22:25], v[174:177], v[220:223], v[22:25]
	v_mfma_f32_16x16x32_bf16 v[18:21], v[182:185], v[220:223], v[18:21]
	v_mfma_f32_16x16x32_bf16 v[6:9], v[174:177], v[228:231], v[6:9]
	v_mfma_f32_16x16x32_bf16 v[2:5], v[182:185], v[228:231], v[2:5]
	v_mfma_f32_16x16x32_bf16 v[54:57], v[178:181], v[194:197], v[54:57]
	v_mfma_f32_16x16x32_bf16 v[50:53], v[186:189], v[194:197], v[50:53]
	v_mfma_f32_16x16x32_bf16 v[38:41], v[178:181], v[216:219], v[38:41]
	v_mfma_f32_16x16x32_bf16 v[34:37], v[186:189], v[216:219], v[34:37]
	v_mfma_f32_16x16x32_bf16 v[22:25], v[178:181], v[224:227], v[22:25]
	v_mfma_f32_16x16x32_bf16 v[18:21], v[186:189], v[224:227], v[18:21]
	v_mfma_f32_16x16x32_bf16 v[6:9], v[178:181], v[232:235], v[6:9]
	v_mfma_f32_16x16x32_bf16 v[2:5], v[186:189], v[232:235], v[2:5]
	s_barrier
	s_add_i32 s22, s22, 2
	s_add_u32 s16, s16, 0x100
	s_addc_u32 s17, s17, 0
	s_add_u32 s14, s14, 0x100
	s_addc_u32 s15, s15, 0
	s_cmp_gt_u32 s22, 29
	s_cbranch_scc0 .LBB0_686
	s_and_b64 vcc, exec, s[50:51]
	s_cbranch_vccz .LBB0_689
	s_barrier

; #define PG8_STAGE(bufoff, gbase, voff) do { _Pragma("unroll") for (int _i = 0; _i < 2; ++_i) \
;         __builtin_amdgcn_global_load_lds((const unsigned*)((const char*)(gbase) + (voff)[_i]), (PG8_LAS unsigned*)(lds + (bufoff) + ldsw + _i * 8192), 16, 0, 0); } while (0)
; #define PG8_LDA(dst, b, h) do { _Pragma("unroll") for (int m = 0; m < 4; ++m) _Pragma("unroll") for (int k = 0; k < 2; ++k) dst[m][k] = *(const PG8_LAS bf16x8*)(lds + PG8_SA(b, h) + aoff + m * 2048 + k * 1024); } while (0)
; #define PG8_LDB(dst, b, h) do { _Pragma("unroll") for (int n = 0; n < 2; ++n) _Pragma("unroll") for (int k = 0; k < 2; ++k) dst[n][k] = *(const PG8_LAS bf16x8*)(lds + PG8_SB(b, h) + boff + n * 2048 + k * 1024); } while (0)
; #define PG8_MMA(ai, bj, At, Bt) do { __builtin_amdgcn_s_setprio(1); _Pragma("unroll") for (int m = 0; m < 4; ++m) _Pragma("unroll") for (int n = 0; n < 2; ++n) _Pragma("unroll") for (int k = 0; k < 2; ++k) \
;         acc[ai][bj][m][n] = __builtin_amdgcn_mfma_f32_16x16x32_bf16(Bt[n][k], At[m][k], acc[ai][bj][m][n], 0, 0, 0); __builtin_amdgcn_s_setprio(0); } while (0)
; #define PG8_WAIT_V(n) asm volatile("s_waitcnt vmcnt(" #n ")" ::: "memory")
; #define PG8_WAIT_L(n) asm volatile("s_waitcnt lgkmcnt(" #n ")" ::: "memory")
; #define PG8_BAR __builtin_amdgcn_s_barrier()
; #define PG8_SCHED __builtin_amdgcn_sched_barrier(0)
; template <class Epi, class Sched, bool ALIGN_EPI = false, bool SP2 = false>
; __device__ __forceinline__ void gemm_phase(PG8_LAS unsigned char* lds, const Gemm g, const Sched& S, const Epi& E) {
;     ...
;             PG8_LDB(B0, 0, 0); PG8_LDB(B1, 0, 1); PG8_SCHED; PG8_LDA(At, 0, 0); PG8_STAGE(PG8_SA(1, 1), a1 + hstep, voffA);
;             PG8_WAIT_V(8); PG8_WAIT_L(0); PG8_BAR; PG8_MMA(0, 0, At, B0); PG8_MMA(0, 1, At, B1); PG8_BAR; PG8_SCHED;
;             PG8_LDA(At, 0, 1); PG8_STAGE(PG8_SB(0, 0), b2, voffB); PG8_STAGE(PG8_SB(0, 1), b2 + hstep, voffB); PG8_STAGE(PG8_SA(0, 0), a2, voffA);
;             PG8_WAIT_V(8); PG8_WAIT_L(0); PG8_BAR; PG8_MMA(1, 0, At, B0); PG8_MMA(1, 1, At, B1); PG8_BAR; PG8_SCHED;
.LBB0_758:
	s_add_u32 s18, s16, 0x100
	s_addc_u32 s19, s17, 0
	s_add_i32 s10, 0, 0x10000
	s_cmpk_eq_i32 s22, 0x7c
	s_cselect_b32 s27, s5, s19
	s_cselect_b32 s26, s7, s18
	s_cselect_b32 s25, s8, s15
	s_cselect_b32 s24, s9, s14
	s_add_i32 s12, 0, 0x14000
	v_add_u32_e32 v160, s10, v216
	v_add_u32_e32 v176, s12, v216
	ds_read_b128 v[148:151], v160
	ds_read_b128 v[152:155], v160 offset:1024
	ds_read_b128 v[156:159], v160 offset:2048
	ds_read_b128 v[160:163], v160 offset:3072
	ds_read_b128 v[164:167], v176
	ds_read_b128 v[168:171], v176 offset:1024
	ds_read_b128 v[172:175], v176 offset:2048
	ds_read_b128 v[176:179], v176 offset:3072
	v_lshl_add_u64 v[200:201], s[16:17], 0, v[144:145]
	s_add_i32 m0, s64, 0xc000
	ds_read_b128 v[180:183], v218
	ds_read_b128 v[184:187], v218 offset:1024
	ds_read_b128 v[188:191], v218 offset:2048
	ds_read_b128 v[192:195], v218 offset:3072
	ds_read_b128 v[196:199], v218 offset:4096
	ds_read_b128 v[220:223], v218 offset:5120
	ds_read_b128 v[224:227], v218 offset:6144
	ds_read_b128 v[228:231], v218 offset:7168
	global_load_lds_dwordx4 v[200:201], off
	v_lshl_add_u64 v[200:201], s[16:17], 0, v[146:147]
	s_add_i32 m0, s64, 0xe000
	s_nop 0
	global_load_lds_dwordx4 v[200:201], off
	s_waitcnt vmcnt(8) lgkmcnt(0)
	s_barrier
	v_mfma_f32_16x16x32_bf16 v[126:129], v[148:151], v[180:183], v[126:129]
	v_mfma_f32_16x16x32_bf16 v[122:125], v[156:159], v[180:183], v[122:125]
	v_mfma_f32_16x16x32_bf16 v[110:113], v[148:151], v[188:191], v[110:113]
	v_mfma_f32_16x16x32_bf16 v[106:109], v[156:159], v[188:191], v[106:109]
	v_mfma_f32_16x16x32_bf16 v[94:97], v[148:151], v[196:199], v[94:97]
	v_mfma_f32_16x16x32_bf16 v[90:93], v[156:159], v[196:199], v[90:93]
	v_mfma_f32_16x16x32_bf16 v[78:81], v[148:151], v[224:227], v[78:81]
	v_mfma_f32_16x16x32_bf16 v[74:77], v[156:159], v[224:227], v[74:77]
	v_mfma_f32_16x16x32_bf16 v[126:129], v[152:155], v[184:187], v[126:129]
	v_mfma_f32_16x16x32_bf16 v[122:125], v[160:163], v[184:187], v[122:125]
	v_mfma_f32_16x16x32_bf16 v[110:113], v[152:155], v[192:195], v[110:113]
	v_mfma_f32_16x16x32_bf16 v[106:109], v[160:163], v[192:195], v[106:109]
	v_mfma_f32_16x16x32_bf16 v[94:97], v[152:155], v[220:223], v[94:97]
	v_mfma_f32_16x16x32_bf16 v[90:93], v[160:163], v[220:223], v[90:93]
	v_mfma_f32_16x16x32_bf16 v[78:81], v[152:155], v[228:231], v[78:81]
	v_mfma_f32_16x16x32_bf16 v[74:77], v[160:163], v[228:231], v[74:77]
	v_mfma_f32_16x16x32_bf16 v[118:121], v[164:167], v[180:183], v[118:121]
	v_mfma_f32_16x16x32_bf16 v[114:117], v[172:175], v[180:183], v[114:117]
	v_mfma_f32_16x16x32_bf16 v[102:105], v[164:167], v[188:191], v[102:105]
	v_mfma_f32_16x16x32_bf16 v[98:101], v[172:175], v[188:191], v[98:101]
	v_mfma_f32_16x16x32_bf16 v[86:89], v[164:167], v[196:199], v[86:89]
	v_mfma_f32_16x16x32_bf16 v[82:85], v[172:175], v[196:199], v[82:85]
	v_mfma_f32_16x16x32_bf16 v[70:73], v[164:167], v[224:227], v[70:73]
	v_mfma_f32_16x16x32_bf16 v[66:69], v[172:175], v[224:227], v[66:69]
	v_mfma_f32_16x16x32_bf16 v[118:121], v[168:171], v[184:187], v[118:121]
	v_mfma_f32_16x16x32_bf16 v[114:117], v[176:179], v[184:187], v[114:117]
	v_mfma_f32_16x16x32_bf16 v[102:105], v[168:171], v[192:195], v[102:105]
	v_mfma_f32_16x16x32_bf16 v[98:101], v[176:179], v[192:195], v[98:101]
	v_mfma_f32_16x16x32_bf16 v[86:89], v[168:171], v[220:223], v[86:89]
	v_mfma_f32_16x16x32_bf16 v[82:85], v[176:179], v[220:223], v[82:85]
	v_mfma_f32_16x16x32_bf16 v[70:73], v[168:171], v[228:231], v[70:73]
	v_mfma_f32_16x16x32_bf16 v[66:69], v[176:179], v[228:231], v[66:69]
	s_barrier
	s_add_i32 s10, s10, s63
	v_lshl_add_u64 v[200:201], s[24:25], 0, v[0:1]
	s_mov_b32 m0, s10
	ds_read_b128 v[180:183], v218 offset:16384
	ds_read_b128 v[184:187], v218 offset:17408
	ds_read_b128 v[188:191], v218 offset:18432
	ds_read_b128 v[192:195], v218 offset:19456
	ds_read_b128 v[196:199], v218 offset:20480
	ds_read_b128 v[220:223], v218 offset:21504
	ds_read_b128 v[224:227], v218 offset:22528
	ds_read_b128 v[228:231], v218 offset:23552
	global_load_lds_dwordx4 v[200:201], off
	s_add_i32 m0, s10, 0x2000
	s_add_u32 s10, s24, 0x200000
	v_lshl_add_u64 v[232:233], s[24:25], 0, v[142:143]
	s_addc_u32 s11, s25, 0
	s_add_i32 s12, s12, s63
	global_load_lds_dwordx4 v[232:233], off
	v_lshl_add_u64 v[234:235], s[10:11], 0, v[0:1]
	s_mov_b32 m0, s12
	v_lshl_add_u64 v[236:237], s[26:27], 0, v[142:143]
	global_load_lds_dwordx4 v[234:235], off
	v_lshl_add_u64 v[234:235], s[10:11], 0, v[142:143]
	s_add_i32 m0, s12, 0x2000
	s_nop 0
	global_load_lds_dwordx4 v[234:235], off
	v_lshl_add_u64 v[234:235], s[26:27], 0, v[0:1]
	s_mov_b32 m0, s64
	s_nop 0
	global_load_lds_dwordx4 v[234:235], off
	s_mov_b32 m0, s65
	s_nop 0
	global_load_lds_dwordx4 v[236:237], off
	s_waitcnt vmcnt(8) lgkmcnt(0)
	s_barrier
; #define PG8_STAGE(bufoff, gbase, voff) do { _Pragma("unroll") for (int _i = 0; _i < 2; ++_i) \
;         __builtin_amdgcn_global_load_lds((const unsigned*)((const char*)(gbase) + (voff)[_i]), (PG8_LAS unsigned*)(lds + (bufoff) + ldsw + _i * 8192), 16, 0, 0); } while (0)
; #define PG8_LDA(dst, b, h) do { _Pragma("unroll") for (int m = 0; m < 4; ++m) _Pragma("unroll") for (int k = 0; k < 2; ++k) dst[m][k] = *(const PG8_LAS bf16x8*)(lds + PG8_SA(b, h) + aoff + m * 2048 + k * 1024); } while (0)
; #define PG8_LDB(dst, b, h) do { _Pragma("unroll") for (int n = 0; n < 2; ++n) _Pragma("unroll") for (int k = 0; k < 2; ++k) dst[n][k] = *(const PG8_LAS bf16x8*)(lds + PG8_SB(b, h) + boff + n * 2048 + k * 1024); } while (0)
; #define PG8_MMA(ai, bj, At, Bt) do { __builtin_amdgcn_s_setprio(1); _Pragma("unroll") for (int m = 0; m < 4; ++m) _Pragma("unroll") for (int n = 0; n < 2; ++n) _Pragma("unroll") for (int k = 0; k < 2; ++k) \
;         acc[ai][bj][m][n] = __builtin_amdgcn_mfma_f32_16x16x32_bf16(Bt[n][k], At[m][k], acc[ai][bj][m][n], 0, 0, 0); __builtin_amdgcn_s_setprio(0); } while (0)
; #define PG8_WAIT_V(n) asm volatile("s_waitcnt vmcnt(" #n ")" ::: "memory")
; #define PG8_WAIT_L(n) asm volatile("s_waitcnt lgkmcnt(" #n ")" ::: "memory")
; #define PG8_BAR __builtin_amdgcn_s_barrier()
; #define PG8_SCHED __builtin_amdgcn_sched_barrier(0)
; template <class Epi, class Sched, bool ALIGN_EPI = false, bool SP2 = false>
; __device__ __forceinline__ void gemm_phase(PG8_LAS unsigned char* lds, const Gemm g, const Sched& S, const Epi& E) {
;     ...
;             PG8_WAIT_V(8); PG8_WAIT_L(0); PG8_BAR; PG8_MMA(1, 0, At, B0); PG8_MMA(1, 1, At, B1); PG8_BAR; PG8_SCHED;
;             PG8_LDB(B0, 1, 0); PG8_LDB(B1, 1, 1); PG8_SCHED; PG8_LDA(At, 1, 0); PG8_STAGE(PG8_SA(0, 1), a2 + hstep, voffA);
;             PG8_WAIT_V(8); PG8_WAIT_L(0); PG8_BAR; PG8_MMA(0, 0, At, B0); PG8_MMA(0, 1, At, B1); PG8_BAR; PG8_SCHED;
;             PG8_LDA(At, 1, 1); PG8_STAGE(PG8_SB(1, 0), b3, voffB); PG8_STAGE(PG8_SB(1, 1), b3 + hstep, voffB); PG8_STAGE(PG8_SA(1, 0), a3, voffA);
;             PG8_WAIT_V(8); PG8_WAIT_L(0); PG8_BAR; PG8_MMA(1, 0, At, B0); PG8_MMA(1, 1, At, B1); PG8_BAR; PG8_SCHED;
	v_mfma_f32_16x16x32_bf16 v[62:65], v[148:151], v[180:183], v[62:65]
	v_mfma_f32_16x16x32_bf16 v[58:61], v[156:159], v[180:183], v[58:61]
	v_mfma_f32_16x16x32_bf16 v[46:49], v[148:151], v[188:191], v[46:49]
	v_mfma_f32_16x16x32_bf16 v[42:45], v[156:159], v[188:191], v[42:45]
	v_mfma_f32_16x16x32_bf16 v[30:33], v[148:151], v[196:199], v[30:33]
	v_mfma_f32_16x16x32_bf16 v[26:29], v[156:159], v[196:199], v[26:29]
	v_mfma_f32_16x16x32_bf16 v[14:17], v[148:151], v[224:227], v[14:17]
	v_mfma_f32_16x16x32_bf16 v[10:13], v[156:159], v[224:227], v[10:13]
	v_mfma_f32_16x16x32_bf16 v[62:65], v[152:155], v[184:187], v[62:65]
	v_mfma_f32_16x16x32_bf16 v[58:61], v[160:163], v[184:187], v[58:61]
	v_mfma_f32_16x16x32_bf16 v[46:49], v[152:155], v[192:195], v[46:49]
	v_mfma_f32_16x16x32_bf16 v[42:45], v[160:163], v[192:195], v[42:45]
	v_mfma_f32_16x16x32_bf16 v[30:33], v[152:155], v[220:223], v[30:33]
	v_mfma_f32_16x16x32_bf16 v[26:29], v[160:163], v[220:223], v[26:29]
	v_mfma_f32_16x16x32_bf16 v[14:17], v[152:155], v[228:231], v[14:17]
	v_mfma_f32_16x16x32_bf16 v[10:13], v[160:163], v[228:231], v[10:13]
	v_mfma_f32_16x16x32_bf16 v[54:57], v[164:167], v[180:183], v[54:57]
	v_mfma_f32_16x16x32_bf16 v[50:53], v[172:175], v[180:183], v[50:53]
	v_mfma_f32_16x16x32_bf16 v[38:41], v[164:167], v[188:191], v[38:41]
	v_mfma_f32_16x16x32_bf16 v[34:37], v[172:175], v[188:191], v[34:37]
	v_mfma_f32_16x16x32_bf16 v[22:25], v[164:167], v[196:199], v[22:25]
	v_mfma_f32_16x16x32_bf16 v[18:21], v[172:175], v[196:199], v[18:21]
	v_mfma_f32_16x16x32_bf16 v[6:9], v[164:167], v[224:227], v[6:9]
	v_mfma_f32_16x16x32_bf16 v[2:5], v[172:175], v[224:227], v[2:5]
	v_mfma_f32_16x16x32_bf16 v[54:57], v[168:171], v[184:187], v[54:57]
	v_mfma_f32_16x16x32_bf16 v[50:53], v[176:179], v[184:187], v[50:53]
	v_mfma_f32_16x16x32_bf16 v[38:41], v[168:171], v[192:195], v[38:41]
	v_mfma_f32_16x16x32_bf16 v[34:37], v[176:179], v[192:195], v[34:37]
	v_mfma_f32_16x16x32_bf16 v[22:25], v[168:171], v[220:223], v[22:25]
	v_mfma_f32_16x16x32_bf16 v[18:21], v[176:179], v[220:223], v[18:21]
	v_mfma_f32_16x16x32_bf16 v[6:9], v[168:171], v[228:231], v[6:9]
	v_mfma_f32_16x16x32_bf16 v[2:5], v[176:179], v[228:231], v[2:5]
	s_barrier
	s_add_i32 s12, 0, 0x18000
	s_add_i32 s13, 0, 0x1c000
	v_add_u32_e32 v160, s12, v216
	v_add_u32_e32 v176, s13, v216
	ds_read_b128 v[148:151], v160
	ds_read_b128 v[152:155], v160 offset:1024
	ds_read_b128 v[156:159], v160 offset:2048
	ds_read_b128 v[160:163], v160 offset:3072
	ds_read_b128 v[164:167], v176
	ds_read_b128 v[168:171], v176 offset:1024
	ds_read_b128 v[172:175], v176 offset:2048
	ds_read_b128 v[176:179], v176 offset:3072
	s_add_u32 s10, s26, 0x200000
	s_addc_u32 s11, s27, 0
	s_mov_b32 m0, s66
	v_lshl_add_u64 v[238:239], s[10:11], 0, v[0:1]
	ds_read_b128 v[180:183], v218 offset:32768
	ds_read_b128 v[184:187], v218 offset:33792
	ds_read_b128 v[188:191], v218 offset:34816
	ds_read_b128 v[192:195], v218 offset:35840
	ds_read_b128 v[196:199], v218 offset:36864
	ds_read_b128 v[220:223], v218 offset:37888
	ds_read_b128 v[224:227], v218 offset:38912
	ds_read_b128 v[228:231], v218 offset:39936
	global_load_lds_dwordx4 v[238:239], off
	v_lshl_add_u64 v[238:239], s[10:11], 0, v[142:143]
	s_mov_b32 m0, s67
	s_nop 0
	global_load_lds_dwordx4 v[238:239], off
	s_waitcnt vmcnt(8) lgkmcnt(0)
	s_barrier
	v_mfma_f32_16x16x32_bf16 v[126:129], v[148:151], v[180:183], v[126:129]
	v_mfma_f32_16x16x32_bf16 v[122:125], v[156:159], v[180:183], v[122:125]
	v_mfma_f32_16x16x32_bf16 v[110:113], v[148:151], v[188:191], v[110:113]
	v_mfma_f32_16x16x32_bf16 v[106:109], v[156:159], v[188:191], v[106:109]
	v_mfma_f32_16x16x32_bf16 v[94:97], v[148:151], v[196:199], v[94:97]
	v_mfma_f32_16x16x32_bf16 v[90:93], v[156:159], v[196:199], v[90:93]
	v_mfma_f32_16x16x32_bf16 v[78:81], v[148:151], v[224:227], v[78:81]
	v_mfma_f32_16x16x32_bf16 v[74:77], v[156:159], v[224:227], v[74:77]
	v_mfma_f32_16x16x32_bf16 v[126:129], v[152:155], v[184:187], v[126:129]
	v_mfma_f32_16x16x32_bf16 v[122:125], v[160:163], v[184:187], v[122:125]
	v_mfma_f32_16x16x32_bf16 v[110:113], v[152:155], v[192:195], v[110:113]
	v_mfma_f32_16x16x32_bf16 v[106:109], v[160:163], v[192:195], v[106:109]
	v_mfma_f32_16x16x32_bf16 v[94:97], v[152:155], v[220:223], v[94:97]
	v_mfma_f32_16x16x32_bf16 v[90:93], v[160:163], v[220:223], v[90:93]
	v_mfma_f32_16x16x32_bf16 v[78:81], v[152:155], v[228:231], v[78:81]
	v_mfma_f32_16x16x32_bf16 v[74:77], v[160:163], v[228:231], v[74:77]
	v_mfma_f32_16x16x32_bf16 v[118:121], v[164:167], v[180:183], v[118:121]
	v_mfma_f32_16x16x32_bf16 v[114:117], v[172:175], v[180:183], v[114:117]
	v_mfma_f32_16x16x32_bf16 v[102:105], v[164:167], v[188:191], v[102:105]
	v_mfma_f32_16x16x32_bf16 v[98:101], v[172:175], v[188:191], v[98:101]
	v_mfma_f32_16x16x32_bf16 v[86:89], v[164:167], v[196:199], v[86:89]
	v_mfma_f32_16x16x32_bf16 v[82:85], v[172:175], v[196:199], v[82:85]
	v_mfma_f32_16x16x32_bf16 v[70:73], v[164:167], v[224:227], v[70:73]
	v_mfma_f32_16x16x32_bf16 v[66:69], v[172:175], v[224:227], v[66:69]
	v_mfma_f32_16x16x32_bf16 v[118:121], v[168:171], v[184:187], v[118:121]
	v_mfma_f32_16x16x32_bf16 v[114:117], v[176:179], v[184:187], v[114:117]
	v_mfma_f32_16x16x32_bf16 v[102:105], v[168:171], v[192:195], v[102:105]
	v_mfma_f32_16x16x32_bf16 v[98:101], v[176:179], v[192:195], v[98:101]
	v_mfma_f32_16x16x32_bf16 v[86:89], v[168:171], v[220:223], v[86:89]
	v_mfma_f32_16x16x32_bf16 v[82:85], v[176:179], v[220:223], v[82:85]
	v_mfma_f32_16x16x32_bf16 v[70:73], v[168:171], v[228:231], v[70:73]
	v_mfma_f32_16x16x32_bf16 v[66:69], v[176:179], v[228:231], v[66:69]
	s_barrier
; #define PG8_STAGE(bufoff, gbase, voff) do { _Pragma("unroll") for (int _i = 0; _i < 2; ++_i) \
;         __builtin_amdgcn_global_load_lds((const unsigned*)((const char*)(gbase) + (voff)[_i]), (PG8_LAS unsigned*)(lds + (bufoff) + ldsw + _i * 8192), 16, 0, 0); } while (0)
; #define PG8_LDA(dst, b, h) do { _Pragma("unroll") for (int m = 0; m < 4; ++m) _Pragma("unroll") for (int k = 0; k < 2; ++k) dst[m][k] = *(const PG8_LAS bf16x8*)(lds + PG8_SA(b, h) + aoff + m * 2048 + k * 1024); } while (0)
; #define PG8_BAR __builtin_amdgcn_s_barrier()
;     __device__ __forceinline__ void operator()(const f32x4 (&acc)[2][2][4][2], const Unit& u, int wr, int wc, int fr, int fq) const {
;     ...
;         for (int ai = 0; ai < 2; ++ai) {
;             u32x2 bv[4][2][2];
; #pragma unroll
;             for (int m = 0; m < 4; ++m) { const size_t off = (size_t)(row0 + ai * HALF + m * 16) * ldc + col0;
; #pragma unroll
;                 for (int bj = 0; bj < 2; ++bj)
; #pragma unroll
;                     for (int n = 0; n < 2; ++n) bv[m][bj][n] = *(const u32x2*)(xb + off + bj * HALF + n * 16); }
;             asm volatile("" ::: "memory");
; #pragma unroll
;             for (int m = 0; m < 4; ++m) {
;                 const int row = row0 + ai * HALF + m * 16;
;                 const size_t off = (size_t)row * ldc + col0;
;                 float s = 0.f;
; #pragma unroll
;                 for (int bj = 0; bj < 2; ++bj)
; #pragma unroll
;                     for (int n = 0; n < 2; ++n) {
;                         const size_t c = off + bj * HALF + n * 16;
;                         const u32x2 w0 = bv[m][bj][n];
;                         const f32x4 b = {__uint_as_float(w0.x << 16), __uint_as_float(w0.x & 0xffff0000u), __uint_as_float(w0.y << 16), __uint_as_float(w0.y & 0xffff0000u)};
;                         const f32x4 o = b + acc[ai][bj][m][n];
;                         if (fin) { *(f32x4*)(outf + c) = o; }
; template <class Epi, class Sched, bool ALIGN_EPI = false, bool SP2 = false>
; __device__ __forceinline__ void gemm_phase(PG8_LAS unsigned char* lds, const Gemm g, const Sched& S, const Epi& E) {
;     ...
;             PG8_LDA(At, 1, 1); PG8_STAGE(PG8_SB(1, 0), b3, voffB); PG8_STAGE(PG8_SB(1, 1), b3 + hstep, voffB); PG8_STAGE(PG8_SA(1, 0), a3, voffA);
;             PG8_WAIT_V(8); PG8_WAIT_L(0); PG8_BAR; PG8_MMA(1, 0, At, B0); PG8_MMA(1, 1, At, B1); PG8_BAR; PG8_SCHED;
	s_add_i32 s10, s12, s63
	v_lshl_add_u64 v[200:201], v[200:201], 0, s[30:31]
	s_mov_b32 m0, s10
	ds_read_b128 v[180:183], v218 offset:49152
	ds_read_b128 v[184:187], v218 offset:50176
	ds_read_b128 v[188:191], v218 offset:51200
	ds_read_b128 v[192:195], v218 offset:52224
	ds_read_b128 v[196:199], v218 offset:53248
	ds_read_b128 v[220:223], v218 offset:54272
	ds_read_b128 v[224:227], v218 offset:55296
	ds_read_b128 v[228:231], v218 offset:56320
	global_load_lds_dwordx4 v[200:201], off
	s_add_i32 m0, s10, 0x2000
	s_add_u32 s10, s24, 0x200080
	v_lshl_add_u64 v[200:201], v[232:233], 0, s[30:31]
	s_addc_u32 s11, s25, 0
	s_add_i32 s12, s13, s63
	global_load_lds_dwordx4 v[200:201], off
	v_lshl_add_u64 v[200:201], s[10:11], 0, v[0:1]
	s_mov_b32 m0, s12
	s_nop 0
	global_load_lds_dwordx4 v[200:201], off
	v_lshl_add_u64 v[200:201], s[10:11], 0, v[142:143]
	s_add_i32 m0, s12, 0x2000
	s_nop 0
	global_load_lds_dwordx4 v[200:201], off
	v_lshl_add_u64 v[200:201], v[234:235], 0, s[30:31]
	s_mov_b32 m0, s68
	s_nop 0
	global_load_lds_dwordx4 v[200:201], off
	v_lshl_add_u64 v[200:201], v[236:237], 0, s[30:31]
	s_mov_b32 m0, s69
	s_nop 0
	global_load_lds_dwordx4 v[200:201], off
	s_waitcnt vmcnt(8) lgkmcnt(0)
	s_barrier
	v_mfma_f32_16x16x32_bf16 v[62:65], v[148:151], v[180:183], v[62:65]
	v_mfma_f32_16x16x32_bf16 v[58:61], v[156:159], v[180:183], v[58:61]
	v_mfma_f32_16x16x32_bf16 v[46:49], v[148:151], v[188:191], v[46:49]
	v_mfma_f32_16x16x32_bf16 v[42:45], v[156:159], v[188:191], v[42:45]
	v_mfma_f32_16x16x32_bf16 v[30:33], v[148:151], v[196:199], v[30:33]
	v_mfma_f32_16x16x32_bf16 v[26:29], v[156:159], v[196:199], v[26:29]
	v_mfma_f32_16x16x32_bf16 v[14:17], v[148:151], v[224:227], v[14:17]
	v_mfma_f32_16x16x32_bf16 v[10:13], v[156:159], v[224:227], v[10:13]
	v_mfma_f32_16x16x32_bf16 v[62:65], v[152:155], v[184:187], v[62:65]
	v_mfma_f32_16x16x32_bf16 v[58:61], v[160:163], v[184:187], v[58:61]
	v_mfma_f32_16x16x32_bf16 v[46:49], v[152:155], v[192:195], v[46:49]
	v_mfma_f32_16x16x32_bf16 v[42:45], v[160:163], v[192:195], v[42:45]
	v_mfma_f32_16x16x32_bf16 v[30:33], v[152:155], v[220:223], v[30:33]
	v_mfma_f32_16x16x32_bf16 v[26:29], v[160:163], v[220:223], v[26:29]
	v_mfma_f32_16x16x32_bf16 v[14:17], v[152:155], v[228:231], v[14:17]
	v_mfma_f32_16x16x32_bf16 v[10:13], v[160:163], v[228:231], v[10:13]
	v_mfma_f32_16x16x32_bf16 v[54:57], v[164:167], v[180:183], v[54:57]
	v_mfma_f32_16x16x32_bf16 v[50:53], v[172:175], v[180:183], v[50:53]
	v_mfma_f32_16x16x32_bf16 v[38:41], v[164:167], v[188:191], v[38:41]
	v_mfma_f32_16x16x32_bf16 v[34:37], v[172:175], v[188:191], v[34:37]
	v_mfma_f32_16x16x32_bf16 v[22:25], v[164:167], v[196:199], v[22:25]
	v_mfma_f32_16x16x32_bf16 v[18:21], v[172:175], v[196:199], v[18:21]
	v_mfma_f32_16x16x32_bf16 v[6:9], v[164:167], v[224:227], v[6:9]
	v_mfma_f32_16x16x32_bf16 v[2:5], v[172:175], v[224:227], v[2:5]
	v_mfma_f32_16x16x32_bf16 v[54:57], v[168:171], v[184:187], v[54:57]
	v_mfma_f32_16x16x32_bf16 v[50:53], v[176:179], v[184:187], v[50:53]
	v_mfma_f32_16x16x32_bf16 v[38:41], v[168:171], v[192:195], v[38:41]
	v_mfma_f32_16x16x32_bf16 v[34:37], v[176:179], v[192:195], v[34:37]
	v_mfma_f32_16x16x32_bf16 v[22:25], v[168:171], v[220:223], v[22:25]
	v_mfma_f32_16x16x32_bf16 v[18:21], v[176:179], v[220:223], v[18:21]
	v_mfma_f32_16x16x32_bf16 v[6:9], v[168:171], v[228:231], v[6:9]
	v_mfma_f32_16x16x32_bf16 v[2:5], v[176:179], v[228:231], v[2:5]
	s_barrier
	s_add_i32 s22, s22, 2
	s_add_u32 s14, s14, 0x100
	s_addc_u32 s15, s15, 0
	s_cmpk_gt_u32 s22, 0x7d
	s_mov_b64 s[16:17], s[18:19]
	s_cbranch_scc0 .LBB0_758
	v_lshl_add_u32 v152, s4, 8, v215
	v_lshl_or_b32 v148, s2, 8, v217
	v_ashrrev_i32_e32 v149, 31, v148
	v_ashrrev_i32_e32 v153, 31, v152
	v_or_b32_e32 v176, 16, v152
	v_lshl_add_u64 v[150:151], v[148:149], 1, s[50:51]
	v_lshlrev_b64 v[154:155], 12, v[152:153]
	v_ashrrev_i32_e32 v177, 31, v176
	v_or_b32_e32 v164, 32, v152
	v_lshl_add_u64 v[198:199], v[150:151], 0, v[154:155]
	v_lshlrev_b64 v[154:155], 12, v[176:177]
	v_ashrrev_i32_e32 v165, 31, v164
	v_lshl_add_u64 v[186:187], v[150:151], 0, v[154:155]
	v_lshlrev_b64 v[154:155], 12, v[164:165]
	v_lshl_add_u64 v[174:175], v[150:151], 0, v[154:155]
	v_or_b32_e32 v154, 48, v152
	v_ashrrev_i32_e32 v155, 31, v154
	v_lshlrev_b64 v[156:157], 12, v[154:155]
	v_lshl_add_u64 v[162:163], v[150:151], 0, v[156:157]
	global_load_dwordx2 v[192:193], v[198:199], off
	global_load_dwordx2 v[196:197], v[198:199], off offset:32
	global_load_dwordx2 v[194:195], v[198:199], off offset:256
	global_load_dwordx2 v[190:191], v[198:199], off offset:288
	global_load_dwordx2 v[188:189], v[186:187], off
	global_load_dwordx2 v[184:185], v[186:187], off offset:32
	global_load_dwordx2 v[182:183], v[186:187], off offset:256
	global_load_dwordx2 v[180:181], v[186:187], off offset:288
	global_load_dwordx2 v[178:179], v[174:175], off
	global_load_dwordx2 v[172:173], v[174:175], off offset:32
	global_load_dwordx2 v[170:171], v[174:175], off offset:256
	global_load_dwordx2 v[168:169], v[174:175], off offset:288
	global_load_dwordx2 v[166:167], v[162:163], off
	global_load_dwordx2 v[160:161], v[162:163], off offset:32
	global_load_dwordx2 v[158:159], v[162:163], off offset:256
	global_load_dwordx2 v[156:157], v[162:163], off offset:288
	v_readlane_b32 s4, v244, 52
	v_readlane_b32 s5, v244, 53
	s_mov_b64 s[16:17], -1
	s_andn2_b64 vcc, exec, s[4:5]
	v_cndmask_b32_e64 v200, 0, 1, s[4:5]
	v_cmp_ne_u32_e64 s[44:45], 1, v200
	v_lshlrev_b64 v[200:201], 11, v[152:153]
	v_lshl_add_u64 v[200:201], v[200:201], 0, v[148:149]
	s_waitcnt vmcnt(0)
	v_lshlrev_b32_e32 v220, 16, v192
	v_and_b32_e32 v221, 0xffff0000, v192
	v_lshlrev_b32_e32 v192, 16, v193
	v_and_b32_e32 v193, 0xffff0000, v193
	v_pk_add_f32 v[128:129], v[128:129], v[192:193]
	v_pk_add_f32 v[126:127], v[126:127], v[220:221]
	v_lshl_add_u64 v[192:193], v[200:201], 2, s[48:49]
	s_cbranch_vccnz .LBB0_761
	s_mov_b64 s[16:17], 0
	global_store_dwordx4 v[192:193], v[126:129], off
